# baseline (speedup 1.0000x reference)
; __device__ __forceinline__ float bf2f(u16 h) { return __uint_as_float(((unsigned)h) << 16); }
; __device__ __forceinline__ u16 f2bf(float f) { return (u16)(cvtpk(f, 0.f) & 0xffffu); }
; template <int DK, bool KBIAS, int ROPE>
; __device__ __forceinline__ void attn_pp(const AttnArgs& a) {
;     ...
;   if constexpr (ROPE == 2) {
; #pragma unroll
;     for (int e = 0; e < 8; ++e) {
;       float c, s; rope_cs(qpos, hi * 8 + e, 32, c, s);
;       const float x1 = bf2f((u16)qr[0][e]), x2 = bf2f((u16)qr[1][e]);
;       qr[0][e] = (short)f2bf(x1 * c - x2 * s); qr[1][e] = (short)f2bf(x2 * c + x1 * s);
;     }
; __global__ void __launch_bounds__(NTHREADS) fwd_megakernel(Params p) {
;     ...
;         const int g16 = xq * 2 + (n >> 6), r = n & 63, b = g16 >> 3, h = g16 & 7, c = (r >> 1) & 1, vh = r & 1;
;         a.qb = 15 - (r >> 2);
;         const size_t t0 = (size_t)b * SEQ;
;         a.Q = proj + t0 * NEP + E_DQ + (h * 2 + c) * 128; a.ldq = NEP;
;         a.K1 = proj + t0 * NEP + E_DK + (h * 2 + c) * 128; a.ldk1 = NEP;
;         a.K2 = nullptr; a.ldk2 = 0;
;         a.V = proj + t0 * NEP + E_DV + h * 256 + vh * 128; a.ldv = NEP;
;         a.O = ob + t0 * 4096 + (h * 2 + c) * 256 + vh * 128; a.ldo = 4096;
;         a.G = nullptr; a.ldg = 0;
;         a.c2 = 0.08838834764831845f * LOG2E;
.Lp4_perm_done:
	s_cmpk_lt_i32 s56, 0x80
	s_cbranch_scc0 .LBB0_1149
	s_ashr_i32 s4, s56, 6
	s_add_i32 s4, s4, s74
	s_ashr_i32 s50, s4, 3
	s_and_b32 s4, s4, 7
	s_bfe_u32 s80, s56, 0x10001
	s_ashr_i32 s51, s50, 31
	s_mul_i32 s52, s50, 0x5e00000
	s_mul_hi_i32 s53, s50, 0x5e00000
	s_add_u32 s5, s42, s52
	s_addc_u32 s34, s43, s53
	s_lshl_b32 s35, s4, 1
	s_or_b32 s57, s35, s80
	s_lshl_b32 s35, s57, 8
	s_add_u32 s35, s5, s35
	s_addc_u32 s38, s34, 0
	s_add_u32 s82, s35, 0x1c80
	s_addc_u32 s83, s38, 0
	s_add_u32 s54, s35, 0x2c80
	s_addc_u32 s55, s38, 0
	s_lshl_b32 s4, s4, 9
	s_add_u32 s4, s5, s4
	s_addc_u32 s5, s34, 0
	s_lshl_b32 s34, s56, 7
	s_and_b32 s34, s34, 0x80
	s_lshl_b32 s75, s34, 1
	s_add_u32 s4, s4, s75
	s_addc_u32 s5, s5, 0
	s_add_u32 s4, s4, 0x3c80
	v_mov_b32_e32 v171, v194
	s_addc_u32 s5, s5, 0
	s_not_b32 s34, s56
	v_readfirstlane_b32 s76, v171
	s_ashr_i32 s77, s76, 1
	s_lshl_b32 s34, s34, 6
	s_andn2_b32 s77, s77, 31
	s_and_b32 s78, s34, 0xf00
	v_and_b32_e32 v170, 31, v171
	s_add_i32 s38, s77, s78
	v_bfe_u32 v8, v171, 5, 1
	v_or_b32_e32 v172, s38, v170
	v_mov_b64_e32 v[0:1], s[82:83]
	v_mad_i64_i32 v[0:1], s[82:83], v172, s61, v[0:1]
	v_lshlrev_b32_e32 v180, 4, v8
	v_lshl_add_u64 v[10:11], v[0:1], 0, v[180:181]
	global_load_dwordx4 v[0:3], v[10:11], off
	global_load_dwordx4 v[4:7], v[10:11], off offset:32
	global_load_dwordx4 v[96:99], v[10:11], off offset:64
	global_load_dwordx4 v[100:103], v[10:11], off offset:96
	global_load_dwordx4 v[104:107], v[10:11], off offset:128
	global_load_dwordx4 v[108:111], v[10:11], off offset:160
	global_load_dwordx4 v[112:115], v[10:11], off offset:192
	global_load_dwordx4 v[116:119], v[10:11], off offset:224
	v_cvt_f32_ubyte0_e32 v9, v180
	v_mul_f32_e32 v9, 0xbd000000, v9
	v_mul_f32_e32 v9, 0x419773da, v9
	v_cvt_f32_i32_e32 v11, v172
	v_exp_f32_e32 v9, v9
	s_ashr_i32 s79, s76, 8
	s_lshl_b32 s83, s79, 5
	v_mov_b64_e32 v[50:51], s[54:55]
	v_mul_f32_e32 v9, v9, v11
	v_mul_f32_e32 v10, 0.15915494, v9
	v_floor_f32_e32 v10, v10
	v_fma_f32 v9, v9, 0.15915494, -v10
	v_cos_f32_e32 v12, v9
	v_sin_f32_e32 v13, v9
	v_mov_b32_e32 v161, v181
	v_mov_b64_e32 v[52:53], s[4:5]
	s_cmp_lg_u32 s79, 1
	s_waitcnt vmcnt(7)
	v_lshlrev_b32_e32 v14, 16, v0
	s_waitcnt vmcnt(6)
	v_lshlrev_b32_e32 v15, 16, v4
	v_pk_mul_f32 v[16:17], v[12:13], v[14:15]
	s_nop 0
	v_sub_f32_e32 v9, v16, v17
	v_mov_b32_e32 v16, v13
	v_mov_b32_e32 v17, v12
	v_pk_mul_f32 v[12:13], v[16:17], v[14:15]
	v_cvt_pk_bf16_f32 v10, v9, v181
	v_and_b32_e32 v15, 0xffff0000, v4
	v_add_f32_e32 v9, v12, v13
	v_or_b32_e32 v12, 2, v180
	v_cvt_f32_ubyte0_e32 v12, v12
	v_mul_f32_e32 v12, 0xbd000000, v12
	v_mul_f32_e32 v12, 0x419773da, v12
	v_exp_f32_e32 v12, v12
	v_and_b32_e32 v14, 0xffff0000, v0
	v_cvt_pk_bf16_f32 v9, v9, v181
	v_mul_f32_e32 v12, v12, v11
	v_mul_f32_e32 v13, 0.15915494, v12
	v_floor_f32_e32 v13, v13
	v_fma_f32 v13, v12, 0.15915494, -v13
	v_cos_f32_e32 v12, v13
	v_sin_f32_e32 v13, v13
	s_nop 0
	v_pk_mul_f32 v[16:17], v[12:13], v[14:15]
	s_nop 0
	v_sub_f32_e32 v0, v16, v17
	v_mov_b32_e32 v16, v13
	v_mov_b32_e32 v17, v12
	v_pk_mul_f32 v[12:13], v[16:17], v[14:15]
	v_cvt_pk_bf16_f32 v4, v0, v181
	v_lshlrev_b32_e32 v17, 16, v5
	v_add_f32_e32 v0, v12, v13
	v_or_b32_e32 v12, 4, v180
	v_cvt_f32_ubyte0_e32 v12, v12
	v_mul_f32_e32 v12, 0xbd000000, v12
	v_mul_f32_e32 v12, 0x419773da, v12
	v_exp_f32_e32 v12, v12
	v_lshlrev_b32_e32 v16, 16, v1
	v_cvt_pk_bf16_f32 v0, v0, v181
	v_mul_f32_e32 v12, v12, v11
	v_mul_f32_e32 v13, 0.15915494, v12
	v_floor_f32_e32 v13, v13
	v_fma_f32 v12, v12, 0.15915494, -v13
	v_cos_f32_e32 v14, v12
	v_sin_f32_e32 v15, v12
	v_mov_b32_e32 v19, v14
	v_pk_mul_f32 v[12:13], v[14:15], v[16:17]
	v_mov_b32_e32 v18, v15
	v_sub_f32_e32 v12, v12, v13
	v_pk_mul_f32 v[14:15], v[18:19], v[16:17]
	v_cvt_pk_bf16_f32 v13, v12, v181
	v_and_b32_e32 v17, 0xffff0000, v5
	v_add_f32_e32 v12, v14, v15
	v_or_b32_e32 v14, 6, v180
	v_cvt_f32_ubyte0_e32 v14, v14
	v_mul_f32_e32 v14, 0xbd000000, v14
	v_mul_f32_e32 v14, 0x419773da, v14
	v_exp_f32_e32 v14, v14
	v_and_b32_e32 v16, 0xffff0000, v1
	v_cvt_pk_bf16_f32 v12, v12, v181
	v_mul_f32_e32 v14, v14, v11
	v_mul_f32_e32 v15, 0.15915494, v14
	v_floor_f32_e32 v15, v15
	v_fma_f32 v15, v14, 0.15915494, -v15
	v_cos_f32_e32 v14, v15
	v_sin_f32_e32 v15, v15
	s_nop 0
	v_pk_mul_f32 v[18:19], v[14:15], v[16:17]
	s_nop 0
	v_sub_f32_e32 v1, v18, v19
	v_mov_b32_e32 v18, v15
	v_mov_b32_e32 v19, v14
	v_pk_mul_f32 v[14:15], v[18:19], v[16:17]
	v_cvt_pk_bf16_f32 v5, v1, v181
	v_lshlrev_b32_e32 v19, 16, v6
	v_add_f32_e32 v1, v14, v15
	v_or_b32_e32 v14, 8, v180
	v_cvt_f32_ubyte0_e32 v14, v14
	v_mul_f32_e32 v14, 0xbd000000, v14
	v_mul_f32_e32 v14, 0x419773da, v14
	v_exp_f32_e32 v14, v14
	v_lshlrev_b32_e32 v18, 16, v2
	v_cvt_pk_bf16_f32 v1, v1, v181
	v_mul_f32_e32 v14, v14, v11
	v_mul_f32_e32 v15, 0.15915494, v14
	v_floor_f32_e32 v15, v15
	v_fma_f32 v14, v14, 0.15915494, -v15
	v_cos_f32_e32 v16, v14
	v_sin_f32_e32 v17, v14
	v_mov_b32_e32 v21, v16
	v_pk_mul_f32 v[14:15], v[16:17], v[18:19]
	v_mov_b32_e32 v20, v17
	v_sub_f32_e32 v14, v14, v15
	v_pk_mul_f32 v[16:17], v[20:21], v[18:19]
	v_cvt_pk_bf16_f32 v15, v14, v181
	v_and_b32_e32 v19, 0xffff0000, v6
; __device__ __forceinline__ float bf2f(u16 h) { return __uint_as_float(((unsigned)h) << 16); }
; __device__ __forceinline__ u16 f2bf(float f) { return (u16)(cvtpk(f, 0.f) & 0xffffu); }
; __device__ __forceinline__ int v_st(int k, int c) { const int kk = (k & ~0xC) | ((k & 4) << 1) | ((k & 8) >> 1); return ((kk >> 3) * 4 + (c >> 5)) * 512 + ((kk & 7) * 32 + (c & 31)) * 2; }
; template <int DK, bool KBIAS, int ROPE>
; __device__ __forceinline__ void attn_pp(const AttnArgs& a) {
;     ...
;   if constexpr (ROPE == 2) {
; #pragma unroll
;     for (int e = 0; e < 8; ++e) {
;       float c, s; rope_cs(qpos, hi * 8 + e, 32, c, s);
;       const float x1 = bf2f((u16)qr[0][e]), x2 = bf2f((u16)qr[1][e]);
;       qr[0][e] = (short)f2bf(x1 * c - x2 * s); qr[1][e] = (short)f2bf(x2 * c + x1 * s);
;     }
;   }
;   const int gt = tid & 255;
;   const int sr = grp * 32 + (gt >> 4), sc = (gt & 15) * 8;
;   const int sr2 = grp * 32 + (gt >> 3), sc2 = (gt & 7) * 8;
;   const int vst0 = v_st(sr, sc);
;   bf16x8 sk0, sk1, sk2, sv0, sv1; float sb = 0.f;
;   bf16x8 tk0, tk1, tk2, tv0, tv1; float tb = 0.f;
;     ...
;   __syncthreads();
;   LOADT(0); LOADT_B(1); WRITET(0, 0); LOADT(2); WRITET_B(1, 1);
;   __syncthreads();
;   if (grp == 1) __syncthreads();
	v_add_f32_e32 v14, v16, v17
	v_or_b32_e32 v16, 10, v180
	v_cvt_f32_ubyte0_e32 v16, v16
	v_mul_f32_e32 v16, 0xbd000000, v16
	v_mul_f32_e32 v16, 0x419773da, v16
	v_exp_f32_e32 v16, v16
	v_and_b32_e32 v18, 0xffff0000, v2
	v_cvt_pk_bf16_f32 v14, v14, v181
	v_mul_f32_e32 v16, v16, v11
	v_mul_f32_e32 v17, 0.15915494, v16
	v_floor_f32_e32 v17, v17
	v_fma_f32 v17, v16, 0.15915494, -v17
	v_cos_f32_e32 v16, v17
	v_sin_f32_e32 v17, v17
	s_nop 0
	v_pk_mul_f32 v[20:21], v[16:17], v[18:19]
	s_nop 0
	v_sub_f32_e32 v2, v20, v21
	v_mov_b32_e32 v20, v17
	v_mov_b32_e32 v21, v16
	v_pk_mul_f32 v[16:17], v[20:21], v[18:19]
	v_cvt_pk_bf16_f32 v6, v2, v181
	v_lshlrev_b32_e32 v21, 16, v7
	v_add_f32_e32 v2, v16, v17
	v_or_b32_e32 v16, 12, v180
	v_cvt_f32_ubyte0_e32 v16, v16
	v_mul_f32_e32 v16, 0xbd000000, v16
	v_mul_f32_e32 v16, 0x419773da, v16
	v_exp_f32_e32 v16, v16
	v_lshlrev_b32_e32 v20, 16, v3
	v_cvt_pk_bf16_f32 v2, v2, v181
	v_mul_f32_e32 v16, v16, v11
	v_mul_f32_e32 v17, 0.15915494, v16
	v_floor_f32_e32 v17, v17
	v_fma_f32 v16, v16, 0.15915494, -v17
	v_cos_f32_e32 v18, v16
	v_sin_f32_e32 v19, v16
	v_mov_b32_e32 v23, v18
	v_pk_mul_f32 v[16:17], v[18:19], v[20:21]
	v_mov_b32_e32 v22, v19
	v_sub_f32_e32 v16, v16, v17
	v_pk_mul_f32 v[18:19], v[22:23], v[20:21]
	v_cvt_pk_bf16_f32 v17, v16, v181
	v_and_b32_e32 v21, 0xffff0000, v7
	v_add_f32_e32 v16, v18, v19
	v_or_b32_e32 v18, 14, v180
	v_cvt_f32_ubyte0_e32 v18, v18
	v_mul_f32_e32 v18, 0xbd000000, v18
	v_mul_f32_e32 v18, 0x419773da, v18
	v_exp_f32_e32 v18, v18
	v_and_b32_e32 v20, 0xffff0000, v3
	v_cvt_pk_bf16_f32 v16, v16, v181
	v_mul_f32_e32 v11, v18, v11
	v_mul_f32_e32 v18, 0.15915494, v11
	v_floor_f32_e32 v18, v18
	v_fma_f32 v11, v11, 0.15915494, -v18
	v_cos_f32_e32 v18, v11
	v_sin_f32_e32 v19, v11
	s_nop 0
	v_pk_mul_f32 v[22:23], v[18:19], v[20:21]
	s_nop 0
	v_sub_f32_e32 v3, v22, v23
	v_mov_b32_e32 v22, v19
	v_mov_b32_e32 v23, v18
	v_pk_mul_f32 v[18:19], v[22:23], v[20:21]
	v_lshrrev_b32_e32 v20, 3, v171
	v_cvt_pk_bf16_f32 v11, v3, v181
	v_add_f32_e32 v3, v18, v19
	v_lshlrev_b32_e32 v18, 3, v171
	v_and_or_b32 v20, v20, 8, s83
	v_and_b32_e32 v19, 0x78, v18
	v_lshrrev_b32_e32 v20, 1, v20
	v_bfe_u32 v18, v18, 5, 2
	v_lshrrev_b32_e32 v21, 5, v171
	v_or_b32_e32 v18, v20, v18
	v_bfe_u32 v20, v171, 4, 2
	v_lshlrev_b32_e32 v160, 1, v19
	v_cvt_pk_bf16_f32 v7, v3, v181
	v_bfe_u32 v3, v171, 4, 4
	v_and_or_b32 v20, v21, 4, v20
	v_and_b32_e32 v19, 48, v160
	v_or_b32_e32 v54, s83, v3
	v_lshl_or_b32 v19, v20, 6, v19
	v_lshl_or_b32 v55, v18, 9, v19
	v_mad_i64_i32 v[18:19], s[54:55], v54, s61, v[50:51]
	v_or_b32_e32 v30, 16, v54
	v_lshl_add_u64 v[18:19], v[18:19], 0, v[160:161]
	v_mad_i64_i32 v[22:23], s[54:55], v30, s61, v[50:51]
	s_barrier
	global_load_dwordx4 v[18:21], v[18:19], off
	v_lshl_add_u64 v[22:23], v[22:23], 0, v[160:161]
	v_mad_i64_i32 v[26:27], s[4:5], v54, s61, v[52:53]
	global_load_dwordx4 v[22:25], v[22:23], off
	v_lshl_add_u64 v[26:27], v[26:27], 0, v[160:161]
	v_mad_i64_i32 v[30:31], s[4:5], v30, s61, v[52:53]
	global_load_dwordx4 v[26:29], v[26:27], off
	v_lshl_add_u64 v[30:31], v[30:31], 0, v[160:161]
	global_load_dwordx4 v[30:33], v[30:31], off
	v_add_u32_e32 v42, 64, v54
	v_add_u32_e32 v46, 0x50, v54
	v_mad_i64_i32 v[34:35], s[4:5], v42, s61, v[50:51]
	v_mad_i64_i32 v[38:39], s[4:5], v46, s61, v[50:51]
	v_mad_i64_i32 v[42:43], s[4:5], v42, s61, v[52:53]
	v_mad_i64_i32 v[46:47], s[4:5], v46, s61, v[52:53]
	s_movk_i32 s4, 0x110
	s_nop 0
	v_mul_lo_u32 v174, v54, s4
	v_lshl_add_u64 v[34:35], v[34:35], 0, v[160:161]
	v_lshl_add_u64 v[38:39], v[38:39], 0, v[160:161]
	v_lshl_add_u64 v[42:43], v[42:43], 0, v[160:161]
	v_lshl_add_u64 v[46:47], v[46:47], 0, v[160:161]
	v_add3_u32 v56, 16, v174, v160
	global_load_dwordx4 v[34:37], v[34:35], off
	v_add_u32_e32 v175, 16, v55
	global_load_dwordx4 v[38:41], v[38:39], off
	s_nop 0
	global_load_dwordx4 v[42:45], v[42:43], off
	s_nop 0
	global_load_dwordx4 v[46:49], v[46:47], off
	s_waitcnt vmcnt(7)
	ds_write_b128 v56, v[18:21]
	s_waitcnt vmcnt(6)
	ds_write_b128 v56, v[22:25] offset:4352
	v_add_u32_e32 v20, 0x80, v54
	v_mad_i64_i32 v[18:19], s[4:5], v20, s61, v[50:51]
	s_waitcnt vmcnt(5)
	ds_write_b128 v175, v[26:29] offset:52224
	s_waitcnt vmcnt(4)
	ds_write_b128 v175, v[30:33] offset:56320
	v_lshl_add_u64 v[18:19], v[18:19], 0, v[160:161]
	v_add_u32_e32 v21, 0x90, v54
	global_load_dwordx4 v[120:123], v[18:19], off
	v_mad_i64_i32 v[18:19], s[4:5], v21, s61, v[50:51]
	v_lshl_add_u64 v[18:19], v[18:19], 0, v[160:161]
	global_load_dwordx4 v[124:127], v[18:19], off
	v_mad_i64_i32 v[18:19], s[4:5], v20, s61, v[52:53]
	v_lshl_add_u64 v[18:19], v[18:19], 0, v[160:161]
	global_load_dwordx4 v[128:131], v[18:19], off
	v_mad_i64_i32 v[18:19], s[4:5], v21, s61, v[52:53]
	v_lshl_add_u64 v[18:19], v[18:19], 0, v[160:161]
	global_load_dwordx4 v[132:135], v[18:19], off
	v_add_u32_e32 v18, 0x10c00, v175
	s_waitcnt vmcnt(7)
	ds_write_b128 v56, v[34:37] offset:17408
	s_waitcnt vmcnt(6)
	ds_write_b128 v56, v[38:41] offset:21760
	s_waitcnt vmcnt(5)
	ds_write_b128 v18, v[42:45]
	s_waitcnt vmcnt(4)
	ds_write_b128 v18, v[46:49] offset:4096
	s_waitcnt lgkmcnt(0)
	s_barrier
	s_cbranch_scc1 .LBB0_1135
	s_barrier
	s_setprio 1

; #define PV(VB) do { PV_D0(VB, 0); PV_D0(VB, 1); PV_D0(VB, 2); PV_D0(VB, 3); } while (0)
; template <int DK, bool KBIAS, int ROPE>
; __device__ __forceinline__ void attn_pp(const AttnArgs& a) {
;     ...
;   for (int t = 0; t < NT; ++t) {
;     __builtin_amdgcn_s_setprio(1);
;     QKT(ks);
;     if (t > 0) PV((vs + 3) & 3);
.LBB0_1136:
	s_mul_i32 s84, s81, 0x4400
	v_add_u32_e32 v183, s84, v177
	ds_read_b128 v[64:67], v183 offset:0
	ds_read_b128 v[68:71], v183 offset:0x2200
	ds_read_b128 v[184:187], v183 offset:32
	ds_read_b128 v[188:191], v183 offset:0x2220
	ds_read_b128 v[196:199], v183 offset:64
	ds_read_b128 v[200:203], v183 offset:0x2240
	ds_read_b128 v[204:207], v183 offset:0x60
	ds_read_b128 v[208:211], v183 offset:0x2260
	ds_read_b128 v[212:215], v183 offset:0x80
	ds_read_b128 v[216:219], v183 offset:0x2280
	ds_read_b128 v[220:223], v183 offset:0xa0
	ds_read_b128 v[224:227], v183 offset:0x22a0
	s_waitcnt lgkmcnt(8)
	s_nop 0
	v_mfma_f32_32x32x16_bf16 v[80:95], v[64:67], v[136:139], 0
	v_mfma_f32_32x32x16_bf16 v[64:79], v[68:71], v[136:139], 0
	v_mfma_f32_32x32x16_bf16 v[80:95], v[184:187], v[140:143], v[80:95]
	ds_read_b128 v[184:187], v183 offset:0xc0
	v_mfma_f32_32x32x16_bf16 v[64:79], v[188:191], v[140:143], v[64:79]
	ds_read_b128 v[188:191], v183 offset:0x22c0
	ds_read_b128 v[228:231], v183 offset:0xe0
	ds_read_b128 v[232:235], v183 offset:0x22e0
	s_waitcnt lgkmcnt(8)
	v_mfma_f32_32x32x16_bf16 v[80:95], v[196:199], v[96:99], v[80:95]
	s_waitcnt lgkmcnt(4)
	v_mfma_f32_32x32x16_bf16 v[64:79], v[200:203], v[96:99], v[64:79]
	v_mfma_f32_32x32x16_bf16 v[80:95], v[204:207], v[100:103], v[80:95]
	v_mfma_f32_32x32x16_bf16 v[64:79], v[208:211], v[100:103], v[64:79]
	v_mfma_f32_32x32x16_bf16 v[80:95], v[212:215], v[104:107], v[80:95]
	s_waitcnt lgkmcnt(0)
	v_mfma_f32_32x32x16_bf16 v[64:79], v[216:219], v[104:107], v[64:79]
	v_mfma_f32_32x32x16_bf16 v[80:95], v[220:223], v[108:111], v[80:95]
	v_mfma_f32_32x32x16_bf16 v[64:79], v[224:227], v[108:111], v[64:79]
	v_mfma_f32_32x32x16_bf16 v[80:95], v[184:187], v[112:115], v[80:95]
	s_cmp_eq_u32 s83, 63
	v_mfma_f32_32x32x16_bf16 v[64:79], v[188:191], v[112:115], v[64:79]
	v_mfma_f32_32x32x16_bf16 v[80:95], v[228:231], v[116:119], v[80:95]
	v_mfma_f32_32x32x16_bf16 v[64:79], v[232:235], v[116:119], v[64:79]
	s_cbranch_scc1 .LBB0_1138
	s_lshl_b32 s34, s80, 14
	s_add_i32 s34, s34, 0xc000
	s_and_b32 s34, s34, 0xc000
	v_add_u32_e32 v183, s34, v176
	ds_read_b64_tr_b16 v[184:185], v183 offset:0
	ds_read_b64_tr_b16 v[186:187], v183 offset:0x800
	ds_read_b64_tr_b16 v[188:189], v183 offset:0x200
	ds_read_b64_tr_b16 v[190:191], v183 offset:0xa00
	ds_read_b64_tr_b16 v[196:197], v183 offset:0x400
	ds_read_b64_tr_b16 v[198:199], v183 offset:0xc00
	ds_read_b64_tr_b16 v[200:201], v183 offset:0x600
	ds_read_b64_tr_b16 v[202:203], v183 offset:0xe00
	ds_read_b64_tr_b16 v[204:205], v183 offset:0x1000
	ds_read_b64_tr_b16 v[206:207], v183 offset:0x1800
	ds_read_b64_tr_b16 v[208:209], v183 offset:0x1200
	ds_read_b64_tr_b16 v[210:211], v183 offset:0x1a00
	s_waitcnt lgkmcnt(8)
	s_nop 0
	v_mfma_f32_32x32x16_bf16 v[48:63], v[156:159], v[184:187], v[48:63]
	ds_read_b64_tr_b16 v[184:185], v183 offset:0x1400
	ds_read_b64_tr_b16 v[186:187], v183 offset:0x1c00
	v_mfma_f32_32x32x16_bf16 v[16:31], v[156:159], v[188:191], v[16:31]
	ds_read_b64_tr_b16 v[188:189], v183 offset:0x1600
	ds_read_b64_tr_b16 v[190:191], v183 offset:0x1e00
	s_waitcnt lgkmcnt(8)
	v_mfma_f32_32x32x16_bf16 v[32:47], v[156:159], v[196:199], v[32:47]
	v_mfma_f32_32x32x16_bf16 v[0:15], v[156:159], v[200:203], v[0:15]
	ds_read_b64_tr_b16 v[156:157], v183 offset:0x2000
	ds_read_b64_tr_b16 v[158:159], v183 offset:0x2800
	ds_read_b64_tr_b16 v[196:197], v183 offset:0x2200
	ds_read_b64_tr_b16 v[198:199], v183 offset:0x2a00
	s_waitcnt lgkmcnt(8)
	v_mfma_f32_32x32x16_bf16 v[48:63], v[152:155], v[204:207], v[48:63]
	ds_read_b64_tr_b16 v[200:201], v183 offset:0x2400
	ds_read_b64_tr_b16 v[202:203], v183 offset:0x2c00
	ds_read_b64_tr_b16 v[204:205], v183 offset:0x2600
	ds_read_b64_tr_b16 v[206:207], v183 offset:0x2e00
	s_waitcnt lgkmcnt(8)
	v_mfma_f32_32x32x16_bf16 v[16:31], v[152:155], v[208:211], v[16:31]
	v_mfma_f32_32x32x16_bf16 v[32:47], v[152:155], v[184:187], v[32:47]
	v_mfma_f32_32x32x16_bf16 v[0:15], v[152:155], v[188:191], v[0:15]
	ds_read_b64_tr_b16 v[152:153], v183 offset:0x3000
	ds_read_b64_tr_b16 v[154:155], v183 offset:0x3800
	ds_read_b64_tr_b16 v[184:185], v183 offset:0x3200
	ds_read_b64_tr_b16 v[186:187], v183 offset:0x3a00
	s_waitcnt lgkmcnt(8)
	v_mfma_f32_32x32x16_bf16 v[48:63], v[148:151], v[156:159], v[48:63]
	ds_read_b64_tr_b16 v[156:157], v183 offset:0x3400
	ds_read_b64_tr_b16 v[158:159], v183 offset:0x3c00
	ds_read_b64_tr_b16 v[188:189], v183 offset:0x3600
	ds_read_b64_tr_b16 v[190:191], v183 offset:0x3e00
	s_waitcnt lgkmcnt(8)
	v_mfma_f32_32x32x16_bf16 v[16:31], v[148:151], v[196:199], v[16:31]
	v_mfma_f32_32x32x16_bf16 v[32:47], v[148:151], v[200:203], v[32:47]
	s_waitcnt lgkmcnt(4)
	v_mfma_f32_32x32x16_bf16 v[0:15], v[148:151], v[204:207], v[0:15]
	v_mfma_f32_32x32x16_bf16 v[48:63], v[144:147], v[152:155], v[48:63]
	s_waitcnt lgkmcnt(0)
	v_mfma_f32_32x32x16_bf16 v[16:31], v[144:147], v[184:187], v[16:31]
	v_mfma_f32_32x32x16_bf16 v[32:47], v[144:147], v[156:159], v[32:47]
	v_mfma_f32_32x32x16_bf16 v[0:15], v[144:147], v[188:191], v[0:15]
; template <int DK, bool KBIAS, int ROPE>
; __device__ __forceinline__ void attn_pp(const AttnArgs& a) {
;     ...
;     __builtin_amdgcn_s_setprio(0);
;     __syncthreads();
;     SOFTMAX(t, vs);
.LBB0_1138:
	s_cmp_le_i32 s83, s38
	s_barrier
	s_cbranch_scc1 .LBB0_1140
	v_add_u32_e32 v144, s83, v161
	v_subrev_u32_e32 v146, 31, v144
	v_subrev_u32_e32 v145, 63, v144
	v_cmp_le_i32_e32 vcc, v146, v172
	s_nop 2
	v_cndmask_b32_e32 v64, v192, v64, vcc
	v_cmp_lt_i32_e32 vcc, v145, v172
	s_nop 1
	v_cndmask_b32_e32 v81, v192, v81, vcc
	v_cmp_le_i32_e32 vcc, v145, v172
	v_subrev_u32_e32 v145, 30, v144
	s_nop 0
	v_cndmask_b32_e32 v80, v192, v80, vcc
	v_cmp_le_i32_e32 vcc, v145, v172
	v_subrev_u32_e32 v145, 61, v144
	s_nop 0
	v_cndmask_b32_e32 v65, v192, v65, vcc
	v_cmp_le_i32_e32 vcc, v145, v172
	v_subrev_u32_e32 v145, 29, v144
	s_nop 0
	v_cndmask_b32_e32 v82, v192, v82, vcc
	v_cmp_le_i32_e32 vcc, v145, v172
	v_subrev_u32_e32 v145, 60, v144
	s_nop 0
	v_cndmask_b32_e32 v66, v192, v66, vcc
	v_cmp_le_i32_e32 vcc, v145, v172
	v_subrev_u32_e32 v145, 28, v144
	s_nop 0
	v_cndmask_b32_e32 v83, v192, v83, vcc
	v_cmp_le_i32_e32 vcc, v145, v172
	v_subrev_u32_e32 v145, 55, v144
	s_nop 0
	v_cndmask_b32_e32 v67, v192, v67, vcc
	v_cmp_le_i32_e32 vcc, v145, v172
	v_subrev_u32_e32 v145, 23, v144
	s_nop 0
	v_cndmask_b32_e32 v84, v192, v84, vcc
	v_cmp_le_i32_e32 vcc, v145, v172
	v_subrev_u32_e32 v145, 54, v144
	s_nop 0
	v_cndmask_b32_e32 v68, v192, v68, vcc
	v_cmp_le_i32_e32 vcc, v145, v172
	v_subrev_u32_e32 v145, 22, v144
	s_nop 0
	v_cndmask_b32_e32 v85, v192, v85, vcc
	v_cmp_le_i32_e32 vcc, v145, v172
	v_subrev_u32_e32 v145, 53, v144
	s_nop 0
	v_cndmask_b32_e32 v69, v192, v69, vcc
	v_cmp_le_i32_e32 vcc, v145, v172
	v_subrev_u32_e32 v145, 21, v144
	s_nop 0
	v_cndmask_b32_e32 v86, v192, v86, vcc
	v_cmp_le_i32_e32 vcc, v145, v172
	v_subrev_u32_e32 v145, 52, v144
	s_nop 0
	v_cndmask_b32_e32 v70, v192, v70, vcc
	v_cmp_le_i32_e32 vcc, v145, v172
	v_subrev_u32_e32 v145, 20, v144
	s_nop 0
	v_cndmask_b32_e32 v87, v192, v87, vcc
	v_cmp_le_i32_e32 vcc, v145, v172
	v_subrev_u32_e32 v145, 47, v144
	s_nop 0
	v_cndmask_b32_e32 v71, v192, v71, vcc
	v_cmp_le_i32_e32 vcc, v145, v172
	v_add_u32_e32 v145, -15, v144
	s_nop 0
	v_cndmask_b32_e32 v88, v192, v88, vcc
	v_cmp_le_i32_e32 vcc, v145, v172
	v_subrev_u32_e32 v145, 46, v144
	s_nop 0
	v_cndmask_b32_e32 v72, v192, v72, vcc
	v_cmp_le_i32_e32 vcc, v145, v172
	v_add_u32_e32 v145, -14, v144
	s_nop 0
	v_cndmask_b32_e32 v89, v192, v89, vcc
	v_cmp_le_i32_e32 vcc, v145, v172
	v_subrev_u32_e32 v145, 45, v144
	s_nop 0
	v_cndmask_b32_e32 v73, v192, v73, vcc
	v_cmp_le_i32_e32 vcc, v145, v172
	v_add_u32_e32 v145, -13, v144
	s_nop 0
	v_cndmask_b32_e32 v90, v192, v90, vcc
	v_cmp_le_i32_e32 vcc, v145, v172
	v_subrev_u32_e32 v145, 44, v144
	s_nop 0
	v_cndmask_b32_e32 v74, v192, v74, vcc
	v_cmp_le_i32_e32 vcc, v145, v172
	v_add_u32_e32 v145, -12, v144
	s_nop 0
	v_cndmask_b32_e32 v91, v192, v91, vcc
	v_cmp_le_i32_e32 vcc, v145, v172
	v_subrev_u32_e32 v145, 39, v144
	s_nop 0
	v_cndmask_b32_e32 v75, v192, v75, vcc
	v_cmp_le_i32_e32 vcc, v145, v172
	v_add_u32_e32 v145, -7, v144
	s_nop 0
	v_cndmask_b32_e32 v92, v192, v92, vcc
	v_cmp_le_i32_e32 vcc, v145, v172
	v_subrev_u32_e32 v145, 38, v144
	s_nop 0
	v_cndmask_b32_e32 v76, v192, v76, vcc
	v_cmp_le_i32_e32 vcc, v145, v172
	v_add_u32_e32 v145, -6, v144
	s_nop 0
	v_cndmask_b32_e32 v93, v192, v93, vcc
	v_cmp_le_i32_e32 vcc, v145, v172
	v_subrev_u32_e32 v145, 37, v144
	s_nop 0
	v_cndmask_b32_e32 v77, v192, v77, vcc
	v_cmp_le_i32_e32 vcc, v145, v172
	v_add_u32_e32 v145, -5, v144
	s_nop 0
	v_cndmask_b32_e32 v94, v192, v94, vcc
	v_cmp_le_i32_e32 vcc, v145, v172
	v_subrev_u32_e32 v145, 36, v144
	v_add_u32_e32 v144, -4, v144
	v_cndmask_b32_e32 v78, v192, v78, vcc
	v_cmp_le_i32_e32 vcc, v145, v172
	s_nop 1
	v_cndmask_b32_e32 v95, v192, v95, vcc
	v_cmp_le_i32_e32 vcc, v144, v172
	s_nop 1
	v_cndmask_b32_e32 v79, v192, v79, vcc

; #define PV(VB) do { PV_D0(VB, 0); PV_D0(VB, 1); PV_D0(VB, 2); PV_D0(VB, 3); } while (0)
; template <int DK, bool KBIAS, int ROPE>
; __device__ __forceinline__ void attn_pp(const AttnArgs& a) {
;     ...
;   PV((vs + 3) & 3);
;   if (grp == 0) __syncthreads();
.LBB0_1150:
	s_setprio 0
	s_lshl_b32 s34, s80, 14
	s_add_i32 s34, s34, 0xc000
	s_and_b32 s34, s34, 0xc000
	v_add_u32_e32 v64, s34, v176
	ds_read_b64_tr_b16 v[66:67], v64 offset:0
	ds_read_b64_tr_b16 v[68:69], v64 offset:0x800
	ds_read_b64_tr_b16 v[70:71], v64 offset:0x200
	ds_read_b64_tr_b16 v[72:73], v64 offset:0xa00
	ds_read_b64_tr_b16 v[74:75], v64 offset:0x400
	ds_read_b64_tr_b16 v[76:77], v64 offset:0xc00
	ds_read_b64_tr_b16 v[78:79], v64 offset:0x600
	ds_read_b64_tr_b16 v[80:81], v64 offset:0xe00
	ds_read_b64_tr_b16 v[82:83], v64 offset:0x1000
	ds_read_b64_tr_b16 v[84:85], v64 offset:0x1800
	ds_read_b64_tr_b16 v[86:87], v64 offset:0x1200
	ds_read_b64_tr_b16 v[88:89], v64 offset:0x1a00
	s_waitcnt lgkmcnt(8)
	s_nop 0
	v_mfma_f32_32x32x16_bf16 v[48:63], v[156:159], v[66:69], v[48:63]
	ds_read_b64_tr_b16 v[66:67], v64 offset:0x1400
	ds_read_b64_tr_b16 v[68:69], v64 offset:0x1c00
	v_mfma_f32_32x32x16_bf16 v[16:31], v[156:159], v[70:73], v[16:31]
	ds_read_b64_tr_b16 v[70:71], v64 offset:0x1600
	ds_read_b64_tr_b16 v[72:73], v64 offset:0x1e00
	s_waitcnt lgkmcnt(8)
	v_mfma_f32_32x32x16_bf16 v[32:47], v[156:159], v[74:77], v[32:47]
	ds_read_b64_tr_b16 v[74:75], v64 offset:0x2000
	ds_read_b64_tr_b16 v[76:77], v64 offset:0x2800
	v_mfma_f32_32x32x16_bf16 v[0:15], v[156:159], v[78:81], v[0:15]
	ds_read_b64_tr_b16 v[78:79], v64 offset:0x2200
	ds_read_b64_tr_b16 v[80:81], v64 offset:0x2a00
	s_waitcnt lgkmcnt(8)
	v_mfma_f32_32x32x16_bf16 v[48:63], v[152:155], v[82:85], v[48:63]
	ds_read_b64_tr_b16 v[82:83], v64 offset:0x2400
	ds_read_b64_tr_b16 v[84:85], v64 offset:0x2c00
	v_mfma_f32_32x32x16_bf16 v[16:31], v[152:155], v[86:89], v[16:31]
	ds_read_b64_tr_b16 v[86:87], v64 offset:0x2600
	ds_read_b64_tr_b16 v[88:89], v64 offset:0x2e00
	s_waitcnt lgkmcnt(8)
	v_mfma_f32_32x32x16_bf16 v[32:47], v[152:155], v[66:69], v[32:47]
	ds_read_b64_tr_b16 v[66:67], v64 offset:0x3000
	ds_read_b64_tr_b16 v[68:69], v64 offset:0x3800
	v_mfma_f32_32x32x16_bf16 v[0:15], v[152:155], v[70:73], v[0:15]
	ds_read_b64_tr_b16 v[70:71], v64 offset:0x3200
	ds_read_b64_tr_b16 v[72:73], v64 offset:0x3a00
	s_waitcnt lgkmcnt(8)
	v_mfma_f32_32x32x16_bf16 v[48:63], v[148:151], v[74:77], v[48:63]
	ds_read_b64_tr_b16 v[74:75], v64 offset:0x3400
	ds_read_b64_tr_b16 v[76:77], v64 offset:0x3c00
	v_mfma_f32_32x32x16_bf16 v[16:31], v[148:151], v[78:81], v[16:31]
	ds_read_b64_tr_b16 v[78:79], v64 offset:0x3600
	ds_read_b64_tr_b16 v[80:81], v64 offset:0x3e00
	s_waitcnt lgkmcnt(8)
	v_mfma_f32_32x32x16_bf16 v[32:47], v[148:151], v[82:85], v[32:47]
	s_waitcnt lgkmcnt(4)
	v_mfma_f32_32x32x16_bf16 v[0:15], v[148:151], v[86:89], v[0:15]
	v_mfma_f32_32x32x16_bf16 v[48:63], v[144:147], v[66:69], v[48:63]
	s_waitcnt lgkmcnt(0)
	v_mfma_f32_32x32x16_bf16 v[16:31], v[144:147], v[70:73], v[16:31]
	v_mfma_f32_32x32x16_bf16 v[32:47], v[144:147], v[74:77], v[32:47]
	s_cmpk_lt_u32 s76, 0x100
	v_mfma_f32_32x32x16_bf16 v[0:15], v[144:147], v[78:81], v[0:15]
	s_cbranch_scc0 .LBB0_1152
	s_barrier

; __device__ __forceinline__ float bf2f(u16 h) { return __uint_as_float(((unsigned)h) << 16); }
; __device__ __forceinline__ u16 f2bf(float f) { return (u16)(cvtpk(f, 0.f) & 0xffffu); }
; template <int DK, bool KBIAS, int ROPE>
; __device__ __forceinline__ void attn_pp(const AttnArgs& a) {
;     ...
;   for (int d0 = 0; d0 < ND; ++d0) qr[d0] = *(const bf16x8*)(a.Q + (size_t)qpos * a.ldq + d0 * 16 + hi * 8);
;   if constexpr (ROPE == 1) {
; #pragma unroll
;     for (int dd = 0; dd < 2; ++dd)
; #pragma unroll
;       for (int e = 0; e < 8; ++e) {
;         float c, s; rope_cs(qpos, dd * 16 + hi * 8 + e, 64, c, s);
;         const float x1 = bf2f((u16)qr[8 + dd][e]), x2 = bf2f((u16)qr[10 + dd][e]);
;         qr[8 + dd][e] = (short)f2bf(x1 * c - x2 * s); qr[10 + dd][e] = (short)f2bf(x2 * c + x1 * s);
;       }
;   }
; __global__ void __launch_bounds__(NTHREADS) fwd_megakernel(Params p) {
;     ...
;       if (n >= 128) {
;         const int m = n - 128, head32 = xq * 4 + (m >> 4), b = head32 >> 4, h = head32 & 15;
;         a.qb = 15 - (m & 15);
;         const size_t t0 = (size_t)b * SEQ;
;         a.Q = qb + t0 * 3072 + h * 192; a.ldq = 3072;
;         a.K1 = kvb + t0 * 4096 + h * 256; a.ldk1 = 4096;
;         a.K2 = proj + t0 * NEP + E_KR; a.ldk2 = NEP;
;         a.V = kvb + t0 * 4096 + h * 256 + 128; a.ldv = 4096;
;         a.O = mixed + t0 * 4096 + h * 128; a.ldo = 4096;
;         a.G = proj + t0 * NEP + E_GA + h * 128; a.ldg = NEP;
;         a.c2 = 0.07216878364870322f * LOG2E;
;     ...
;         attn_pp<192, false, 1>(a);
.LBB0_1283:
	s_add_i32 s4, s56, 0xffffff80
	s_lshr_b32 s57, s4, 4
	s_add_i32 s4, s57, s73
	s_lshr_b32 s38, s4, 4
	s_and_b32 s76, s4, 15
	s_mul_i32 s5, s38, 0x1800000
	s_mul_hi_u32 s4, s38, 0x1800000
	s_add_u32 s5, s14, s5
	s_addc_u32 s4, s15, s4
	s_mul_i32 s34, s76, 0x180
	s_add_u32 s54, s5, s34
	s_addc_u32 s55, s4, 0
	s_lshl_b64 s[4:5], s[38:39], 25
	s_add_u32 s4, s18, s4
	s_addc_u32 s5, s19, s5
	s_lshl_b32 s34, s76, 9
	s_add_u32 s4, s4, s34
	s_addc_u32 s5, s5, 0
	s_mul_i32 s35, s38, 0x5e00000
	s_mul_hi_u32 s34, s38, 0x5e00000
	s_add_u32 s52, s42, s35
	v_mov_b32_e32 v196, v194
	s_addc_u32 s53, s43, s34
	s_not_b32 s34, s56
	v_readfirstlane_b32 s77, v196
	s_ashr_i32 s78, s77, 1
	s_lshl_b32 s34, s34, 8
	s_andn2_b32 s78, s78, 31
	s_and_b32 s56, s34, 0xf00
	v_and_b32_e32 v195, 31, v196
	s_add_i32 s75, s78, s56
	v_bfe_u32 v16, v196, 5, 1
	v_or_b32_e32 v197, s75, v195
	v_mov_b64_e32 v[0:1], s[54:55]
	s_movk_i32 s34, 0x1800
	v_mad_i64_i32 v[0:1], s[54:55], v197, s34, v[0:1]
	v_lshlrev_b32_e32 v180, 4, v16
	v_lshl_add_u64 v[4:5], v[0:1], 0, v[180:181]
	global_load_dwordx4 v[96:99], v[4:5], off
	global_load_dwordx4 v[100:103], v[4:5], off offset:32
	global_load_dwordx4 v[104:107], v[4:5], off offset:64
	global_load_dwordx4 v[108:111], v[4:5], off offset:96
	global_load_dwordx4 v[112:115], v[4:5], off offset:128
	global_load_dwordx4 v[116:119], v[4:5], off offset:160
	global_load_dwordx4 v[120:123], v[4:5], off offset:192
	global_load_dwordx4 v[124:127], v[4:5], off offset:224
	global_load_dwordx4 v[8:11], v[4:5], off offset:256
	global_load_dwordx4 v[0:3], v[4:5], off offset:288
	global_load_dwordx4 v[12:15], v[4:5], off offset:320
	s_nop 0
	global_load_dwordx4 v[4:7], v[4:5], off offset:352
	v_cvt_f32_ubyte0_e32 v17, v180
	v_mul_f32_e32 v17, 0xbc800000, v17
	v_mul_f32_e32 v17, 0x419773da, v17
	v_cvt_f32_i32_e32 v19, v197
	v_exp_f32_e32 v17, v17
	s_ashr_i32 s54, s77, 8
	s_lshl_b32 s82, s54, 5
	v_mov_b32_e32 v183, v181
	v_mul_f32_e32 v17, v17, v19
	v_mul_f32_e32 v18, 0.15915494, v17
	v_floor_f32_e32 v18, v18
	v_fma_f32 v17, v17, 0.15915494, -v18
	v_cos_f32_e32 v20, v17
	v_sin_f32_e32 v21, v17
	v_mov_b64_e32 v[80:81], s[52:53]
	v_mov_b32_e32 v185, v181
	s_cmp_lg_u32 s54, 1
	s_waitcnt vmcnt(3)
	v_lshlrev_b32_e32 v22, 16, v8
	s_waitcnt vmcnt(1)
	v_lshlrev_b32_e32 v23, 16, v12
	v_pk_mul_f32 v[24:25], v[20:21], v[22:23]
	s_nop 0
	v_sub_f32_e32 v17, v24, v25
	v_mov_b32_e32 v24, v21
	v_mov_b32_e32 v25, v20
	v_pk_mul_f32 v[20:21], v[24:25], v[22:23]
	v_cvt_pk_bf16_f32 v18, v17, v181
	v_and_b32_e32 v23, 0xffff0000, v12
	v_add_f32_e32 v17, v20, v21
	v_or_b32_e32 v20, 2, v180
	v_cvt_f32_ubyte0_e32 v20, v20
	v_mul_f32_e32 v20, 0xbc800000, v20
	v_mul_f32_e32 v20, 0x419773da, v20
	v_exp_f32_e32 v20, v20
	v_and_b32_e32 v22, 0xffff0000, v8
	v_cvt_pk_bf16_f32 v17, v17, v181
	v_mul_f32_e32 v20, v20, v19
	v_mul_f32_e32 v21, 0.15915494, v20
	v_floor_f32_e32 v21, v21
	v_fma_f32 v21, v20, 0.15915494, -v21
	v_cos_f32_e32 v20, v21
	v_sin_f32_e32 v21, v21
	s_nop 0
	v_pk_mul_f32 v[24:25], v[20:21], v[22:23]
	s_nop 0
	v_sub_f32_e32 v8, v24, v25
	v_mov_b32_e32 v24, v21
	v_mov_b32_e32 v25, v20
	v_pk_mul_f32 v[20:21], v[24:25], v[22:23]
	v_cvt_pk_bf16_f32 v12, v8, v181
	v_lshlrev_b32_e32 v25, 16, v13
	v_add_f32_e32 v8, v20, v21
	v_or_b32_e32 v20, 4, v180
	v_cvt_f32_ubyte0_e32 v20, v20
	v_mul_f32_e32 v20, 0xbc800000, v20
	v_mul_f32_e32 v20, 0x419773da, v20
	v_exp_f32_e32 v20, v20
	v_lshlrev_b32_e32 v24, 16, v9
	v_cvt_pk_bf16_f32 v8, v8, v181
	v_mul_f32_e32 v20, v20, v19
	v_mul_f32_e32 v21, 0.15915494, v20
	v_floor_f32_e32 v21, v21
	v_fma_f32 v20, v20, 0.15915494, -v21
	v_cos_f32_e32 v22, v20
	v_sin_f32_e32 v23, v20
	v_mov_b32_e32 v27, v22
	v_pk_mul_f32 v[20:21], v[22:23], v[24:25]
	v_mov_b32_e32 v26, v23
	v_sub_f32_e32 v20, v20, v21
	v_pk_mul_f32 v[22:23], v[26:27], v[24:25]
	v_cvt_pk_bf16_f32 v21, v20, v181
	v_and_b32_e32 v25, 0xffff0000, v13
	v_add_f32_e32 v20, v22, v23
	v_or_b32_e32 v22, 6, v180
	v_cvt_f32_ubyte0_e32 v22, v22
	v_mul_f32_e32 v22, 0xbc800000, v22
	v_mul_f32_e32 v22, 0x419773da, v22
	v_exp_f32_e32 v22, v22
	v_and_b32_e32 v24, 0xffff0000, v9
	v_cvt_pk_bf16_f32 v20, v20, v181
	v_mul_f32_e32 v22, v22, v19
	v_mul_f32_e32 v23, 0.15915494, v22
	v_floor_f32_e32 v23, v23
	v_fma_f32 v23, v22, 0.15915494, -v23
	v_cos_f32_e32 v22, v23
	v_sin_f32_e32 v23, v23
	s_nop 0
	v_pk_mul_f32 v[26:27], v[22:23], v[24:25]
	s_nop 0
	v_sub_f32_e32 v9, v26, v27
	v_mov_b32_e32 v26, v23
	v_mov_b32_e32 v27, v22
	v_pk_mul_f32 v[22:23], v[26:27], v[24:25]
	v_cvt_pk_bf16_f32 v13, v9, v181
	v_lshlrev_b32_e32 v27, 16, v14
	v_add_f32_e32 v9, v22, v23
	v_or_b32_e32 v22, 8, v180
	v_cvt_f32_ubyte0_e32 v22, v22
	v_mul_f32_e32 v22, 0xbc800000, v22
	v_mul_f32_e32 v22, 0x419773da, v22
	v_exp_f32_e32 v22, v22
	v_lshlrev_b32_e32 v26, 16, v10
	v_cvt_pk_bf16_f32 v9, v9, v181
	v_mul_f32_e32 v22, v22, v19
	v_mul_f32_e32 v23, 0.15915494, v22
	v_floor_f32_e32 v23, v23
	v_fma_f32 v22, v22, 0.15915494, -v23
	v_cos_f32_e32 v24, v22
	v_sin_f32_e32 v25, v22
	v_mov_b32_e32 v29, v24
	v_pk_mul_f32 v[22:23], v[24:25], v[26:27]
	v_mov_b32_e32 v28, v25
	v_sub_f32_e32 v22, v22, v23
	v_pk_mul_f32 v[24:25], v[28:29], v[26:27]
	v_cvt_pk_bf16_f32 v23, v22, v181
	v_and_b32_e32 v27, 0xffff0000, v14
	v_add_f32_e32 v22, v24, v25
	v_or_b32_e32 v24, 10, v180
	v_cvt_f32_ubyte0_e32 v24, v24
	v_mul_f32_e32 v24, 0xbc800000, v24
	v_mul_f32_e32 v24, 0x419773da, v24
	v_exp_f32_e32 v24, v24
	v_and_b32_e32 v26, 0xffff0000, v10
	v_cvt_pk_bf16_f32 v22, v22, v181
	v_mul_f32_e32 v24, v24, v19
	v_mul_f32_e32 v25, 0.15915494, v24
	v_floor_f32_e32 v25, v25
	v_fma_f32 v25, v24, 0.15915494, -v25
	v_cos_f32_e32 v24, v25
	v_sin_f32_e32 v25, v25
; __device__ __forceinline__ float bf2f(u16 h) { return __uint_as_float(((unsigned)h) << 16); }
; __device__ __forceinline__ u16 f2bf(float f) { return (u16)(cvtpk(f, 0.f) & 0xffffu); }
; template <int DK, bool KBIAS, int ROPE>
; __device__ __forceinline__ void attn_pp(const AttnArgs& a) {
;     ...
;   if constexpr (ROPE == 1) {
; #pragma unroll
;     for (int dd = 0; dd < 2; ++dd)
; #pragma unroll
;       for (int e = 0; e < 8; ++e) {
;         float c, s; rope_cs(qpos, dd * 16 + hi * 8 + e, 64, c, s);
;         const float x1 = bf2f((u16)qr[8 + dd][e]), x2 = bf2f((u16)qr[10 + dd][e]);
;         qr[8 + dd][e] = (short)f2bf(x1 * c - x2 * s); qr[10 + dd][e] = (short)f2bf(x2 * c + x1 * s);
;       }
;   }
	s_nop 0
	v_pk_mul_f32 v[28:29], v[24:25], v[26:27]
	s_nop 0
	v_sub_f32_e32 v10, v28, v29
	v_mov_b32_e32 v28, v25
	v_mov_b32_e32 v29, v24
	v_pk_mul_f32 v[24:25], v[28:29], v[26:27]
	v_cvt_pk_bf16_f32 v14, v10, v181
	v_lshlrev_b32_e32 v29, 16, v15
	v_add_f32_e32 v10, v24, v25
	v_or_b32_e32 v24, 12, v180
	v_cvt_f32_ubyte0_e32 v24, v24
	v_mul_f32_e32 v24, 0xbc800000, v24
	v_mul_f32_e32 v24, 0x419773da, v24
	v_exp_f32_e32 v24, v24
	v_lshlrev_b32_e32 v28, 16, v11
	v_cvt_pk_bf16_f32 v10, v10, v181
	v_mul_f32_e32 v24, v24, v19
	v_mul_f32_e32 v25, 0.15915494, v24
	v_floor_f32_e32 v25, v25
	v_fma_f32 v24, v24, 0.15915494, -v25
	v_cos_f32_e32 v26, v24
	v_sin_f32_e32 v27, v24
	v_mov_b32_e32 v31, v26
	v_pk_mul_f32 v[24:25], v[26:27], v[28:29]
	v_mov_b32_e32 v30, v27
	v_sub_f32_e32 v24, v24, v25
	v_pk_mul_f32 v[26:27], v[30:31], v[28:29]
	v_cvt_pk_bf16_f32 v25, v24, v181
	v_and_b32_e32 v29, 0xffff0000, v15
	v_add_f32_e32 v24, v26, v27
	v_or_b32_e32 v26, 14, v180
	v_cvt_f32_ubyte0_e32 v26, v26
	v_mul_f32_e32 v26, 0xbc800000, v26
	v_mul_f32_e32 v26, 0x419773da, v26
	v_exp_f32_e32 v26, v26
	v_and_b32_e32 v28, 0xffff0000, v11
	v_cvt_pk_bf16_f32 v24, v24, v181
	v_mul_f32_e32 v26, v26, v19
	v_mul_f32_e32 v27, 0.15915494, v26
	v_floor_f32_e32 v27, v27
	v_fma_f32 v27, v26, 0.15915494, -v27
	v_cos_f32_e32 v26, v27
	v_sin_f32_e32 v27, v27
	s_nop 0
	v_pk_mul_f32 v[30:31], v[26:27], v[28:29]
	s_nop 0
	v_sub_f32_e32 v11, v30, v31
	v_mov_b32_e32 v30, v27
	v_mov_b32_e32 v31, v26
	v_pk_mul_f32 v[26:27], v[30:31], v[28:29]
	v_cvt_pk_bf16_f32 v15, v11, v181
	s_waitcnt vmcnt(0)
	v_lshlrev_b32_e32 v31, 16, v4
	v_add_f32_e32 v11, v26, v27
	v_or_b32_e32 v26, 32, v180
	v_cvt_f32_ubyte0_e32 v26, v26
	v_mul_f32_e32 v26, 0xbc800000, v26
	v_mul_f32_e32 v26, 0x419773da, v26
	v_exp_f32_e32 v26, v26
	v_lshlrev_b32_e32 v30, 16, v0
	v_cvt_pk_bf16_f32 v11, v11, v181
	v_mul_f32_e32 v26, v26, v19
	v_mul_f32_e32 v27, 0.15915494, v26
	v_floor_f32_e32 v27, v27
	v_fma_f32 v26, v26, 0.15915494, -v27
	v_cos_f32_e32 v28, v26
	v_sin_f32_e32 v29, v26
	v_mov_b32_e32 v33, v28
	v_pk_mul_f32 v[26:27], v[28:29], v[30:31]
	v_mov_b32_e32 v32, v29
	v_sub_f32_e32 v26, v26, v27
	v_pk_mul_f32 v[28:29], v[32:33], v[30:31]
	v_cvt_pk_bf16_f32 v27, v26, v181
	v_and_b32_e32 v31, 0xffff0000, v4
	v_add_f32_e32 v26, v28, v29
	v_or_b32_e32 v28, 34, v180
	v_cvt_f32_ubyte0_e32 v28, v28
	v_mul_f32_e32 v28, 0xbc800000, v28
	v_mul_f32_e32 v28, 0x419773da, v28
	v_exp_f32_e32 v28, v28
	v_and_b32_e32 v30, 0xffff0000, v0
	v_cvt_pk_bf16_f32 v26, v26, v181
	v_mul_f32_e32 v28, v28, v19
	v_mul_f32_e32 v29, 0.15915494, v28
	v_floor_f32_e32 v29, v29
	v_fma_f32 v29, v28, 0.15915494, -v29
	v_cos_f32_e32 v28, v29
	v_sin_f32_e32 v29, v29
	s_nop 0
	v_pk_mul_f32 v[32:33], v[28:29], v[30:31]
	s_nop 0
	v_sub_f32_e32 v0, v32, v33
	v_mov_b32_e32 v32, v29
	v_mov_b32_e32 v33, v28
	v_pk_mul_f32 v[28:29], v[32:33], v[30:31]
	v_cvt_pk_bf16_f32 v4, v0, v181
	v_lshlrev_b32_e32 v33, 16, v5
	v_add_f32_e32 v0, v28, v29
	v_or_b32_e32 v28, 36, v180
	v_cvt_f32_ubyte0_e32 v28, v28
	v_mul_f32_e32 v28, 0xbc800000, v28
	v_mul_f32_e32 v28, 0x419773da, v28
	v_exp_f32_e32 v28, v28
	v_lshlrev_b32_e32 v32, 16, v1
	v_cvt_pk_bf16_f32 v0, v0, v181
	v_mul_f32_e32 v28, v28, v19
	v_mul_f32_e32 v29, 0.15915494, v28
	v_floor_f32_e32 v29, v29
	v_fma_f32 v28, v28, 0.15915494, -v29
	v_cos_f32_e32 v30, v28
	v_sin_f32_e32 v31, v28
	v_mov_b32_e32 v35, v30
	v_pk_mul_f32 v[28:29], v[30:31], v[32:33]
	v_mov_b32_e32 v34, v31
	v_sub_f32_e32 v28, v28, v29
	v_pk_mul_f32 v[30:31], v[34:35], v[32:33]
	v_cvt_pk_bf16_f32 v29, v28, v181
	v_and_b32_e32 v33, 0xffff0000, v5
	v_add_f32_e32 v28, v30, v31
	v_or_b32_e32 v30, 38, v180
	v_cvt_f32_ubyte0_e32 v30, v30
	v_mul_f32_e32 v30, 0xbc800000, v30
	v_mul_f32_e32 v30, 0x419773da, v30
	v_exp_f32_e32 v30, v30
	v_and_b32_e32 v32, 0xffff0000, v1
	v_cvt_pk_bf16_f32 v28, v28, v181
	v_mul_f32_e32 v30, v30, v19
	v_mul_f32_e32 v31, 0.15915494, v30
	v_floor_f32_e32 v31, v31
	v_fma_f32 v31, v30, 0.15915494, -v31
	v_cos_f32_e32 v30, v31
	v_sin_f32_e32 v31, v31
	s_nop 0
	v_pk_mul_f32 v[34:35], v[30:31], v[32:33]
	s_nop 0
	v_sub_f32_e32 v1, v34, v35
	v_mov_b32_e32 v34, v31
	v_mov_b32_e32 v35, v30
	v_pk_mul_f32 v[30:31], v[34:35], v[32:33]
	v_cvt_pk_bf16_f32 v5, v1, v181
	v_lshlrev_b32_e32 v35, 16, v6
	v_add_f32_e32 v1, v30, v31
	v_or_b32_e32 v30, 40, v180
	v_cvt_f32_ubyte0_e32 v30, v30
	v_mul_f32_e32 v30, 0xbc800000, v30
	v_mul_f32_e32 v30, 0x419773da, v30
	v_exp_f32_e32 v30, v30
	v_lshlrev_b32_e32 v34, 16, v2
	v_cvt_pk_bf16_f32 v1, v1, v181
	v_mul_f32_e32 v30, v30, v19
	v_mul_f32_e32 v31, 0.15915494, v30
	v_floor_f32_e32 v31, v31
	v_fma_f32 v30, v30, 0.15915494, -v31
	v_cos_f32_e32 v32, v30
	v_sin_f32_e32 v33, v30
	v_mov_b32_e32 v37, v32
	v_pk_mul_f32 v[30:31], v[32:33], v[34:35]
	v_mov_b32_e32 v36, v33
	v_sub_f32_e32 v30, v30, v31
	v_pk_mul_f32 v[32:33], v[36:37], v[34:35]
	v_cvt_pk_bf16_f32 v31, v30, v181
	v_and_b32_e32 v35, 0xffff0000, v6
	v_add_f32_e32 v30, v32, v33
	v_or_b32_e32 v32, 42, v180
	v_cvt_f32_ubyte0_e32 v32, v32
	v_mul_f32_e32 v32, 0xbc800000, v32
	v_mul_f32_e32 v32, 0x419773da, v32
	v_exp_f32_e32 v32, v32
	v_and_b32_e32 v34, 0xffff0000, v2
	v_cvt_pk_bf16_f32 v30, v30, v181
	v_mul_f32_e32 v32, v32, v19
	v_mul_f32_e32 v33, 0.15915494, v32
	v_floor_f32_e32 v33, v33
	v_fma_f32 v33, v32, 0.15915494, -v33
	v_cos_f32_e32 v32, v33
; __device__ __forceinline__ float bf2f(u16 h) { return __uint_as_float(((unsigned)h) << 16); }
; __device__ __forceinline__ u16 f2bf(float f) { return (u16)(cvtpk(f, 0.f) & 0xffffu); }
; __device__ __forceinline__ int v_st(int k, int c) { const int kk = (k & ~0xC) | ((k & 4) << 1) | ((k & 8) >> 1); return ((kk >> 3) * 4 + (c >> 5)) * 512 + ((kk & 7) * 32 + (c & 31)) * 2; }
; template <int DK, bool KBIAS, int ROPE>
; __device__ __forceinline__ void attn_pp(const AttnArgs& a) {
;     ...
;       for (int e = 0; e < 8; ++e) {
;         float c, s; rope_cs(qpos, dd * 16 + hi * 8 + e, 64, c, s);
;         const float x1 = bf2f((u16)qr[8 + dd][e]), x2 = bf2f((u16)qr[10 + dd][e]);
;         qr[8 + dd][e] = (short)f2bf(x1 * c - x2 * s); qr[10 + dd][e] = (short)f2bf(x2 * c + x1 * s);
;       }
;   }
;   if constexpr (ROPE == 2) {
; #pragma unroll
;     for (int e = 0; e < 8; ++e) {
;       float c, s; rope_cs(qpos, hi * 8 + e, 32, c, s);
;       const float x1 = bf2f((u16)qr[0][e]), x2 = bf2f((u16)qr[1][e]);
;       qr[0][e] = (short)f2bf(x1 * c - x2 * s); qr[1][e] = (short)f2bf(x2 * c + x1 * s);
;     }
;   }
;   const int gt = tid & 255;
;   const int sr = grp * 32 + (gt >> 4), sc = (gt & 15) * 8;
;   const int sr2 = grp * 32 + (gt >> 3), sc2 = (gt & 7) * 8;
;   const int vst0 = v_st(sr, sc);
;   bf16x8 sk0, sk1, sk2, sv0, sv1; float sb = 0.f;
;   bf16x8 tk0, tk1, tk2, tv0, tv1; float tb = 0.f;
;     ...
;   __syncthreads();
;   LOADT(0); LOADT_B(1); WRITET(0, 0); LOADT(2); WRITET_B(1, 1);
;   __syncthreads();
;   if (grp == 1) __syncthreads();
	v_sin_f32_e32 v33, v33
	s_nop 0
	v_pk_mul_f32 v[36:37], v[32:33], v[34:35]
	s_nop 0
	v_sub_f32_e32 v2, v36, v37
	v_mov_b32_e32 v36, v33
	v_mov_b32_e32 v37, v32
	v_pk_mul_f32 v[32:33], v[36:37], v[34:35]
	v_cvt_pk_bf16_f32 v6, v2, v181
	v_lshlrev_b32_e32 v37, 16, v7
	v_add_f32_e32 v2, v32, v33
	v_or_b32_e32 v32, 44, v180
	v_cvt_f32_ubyte0_e32 v32, v32
	v_mul_f32_e32 v32, 0xbc800000, v32
	v_mul_f32_e32 v32, 0x419773da, v32
	v_exp_f32_e32 v32, v32
	v_lshlrev_b32_e32 v36, 16, v3
	v_cvt_pk_bf16_f32 v2, v2, v181
	v_mul_f32_e32 v32, v32, v19
	v_mul_f32_e32 v33, 0.15915494, v32
	v_floor_f32_e32 v33, v33
	v_fma_f32 v32, v32, 0.15915494, -v33
	v_cos_f32_e32 v34, v32
	v_sin_f32_e32 v35, v32
	v_mov_b32_e32 v39, v34
	v_pk_mul_f32 v[32:33], v[34:35], v[36:37]
	v_mov_b32_e32 v38, v35
	v_sub_f32_e32 v32, v32, v33
	v_pk_mul_f32 v[34:35], v[38:39], v[36:37]
	v_cvt_pk_bf16_f32 v33, v32, v181
	v_and_b32_e32 v39, 0xffff0000, v7
	v_add_f32_e32 v32, v34, v35
	v_or_b32_e32 v34, 46, v180
	v_cvt_f32_ubyte0_e32 v34, v34
	v_mul_f32_e32 v34, 0xbc800000, v34
	v_mul_f32_e32 v34, 0x419773da, v34
	v_exp_f32_e32 v34, v34
	v_and_b32_e32 v38, 0xffff0000, v3
	v_bfe_u32 v7, v196, 3, 5
	v_cvt_pk_bf16_f32 v32, v32, v181
	v_mul_f32_e32 v19, v34, v19
	v_mul_f32_e32 v34, 0.15915494, v19
	v_floor_f32_e32 v34, v34
	v_fma_f32 v19, v19, 0.15915494, -v34
	v_cos_f32_e32 v36, v19
	v_sin_f32_e32 v37, v19
	v_or_b32_e32 v82, s82, v7
	v_add_u32_e32 v64, 64, v82
	v_mov_b32_e32 v41, v36
	v_pk_mul_f32 v[34:35], v[36:37], v[38:39]
	v_mov_b32_e32 v40, v37
	v_sub_f32_e32 v3, v34, v35
	v_pk_mul_f32 v[36:37], v[40:41], v[38:39]
	v_lshlrev_b32_e32 v35, 3, v196
	v_cvt_pk_bf16_f32 v34, v3, v181
	v_add_f32_e32 v3, v36, v37
	v_and_b32_e32 v36, 0x78, v35
	v_and_or_b32 v37, v7, 8, s82
	v_lshrrev_b32_e32 v38, 5, v196
	v_cvt_pk_bf16_f32 v19, v3, v181
	v_bfe_u32 v3, v196, 4, 4
	v_and_b32_e32 v38, 4, v38
	v_lshrrev_b32_e32 v37, 1, v37
	v_bfe_u32 v35, v35, 5, 2
	v_lshlrev_b32_e32 v182, 1, v36
	v_or_b32_e32 v76, s82, v3
	v_or_b32_e32 v35, v37, v35
	v_and_or_b32 v37, v3, 3, v38
	v_and_b32_e32 v36, 48, v182
	v_lshl_or_b32 v36, v37, 6, v36
	v_ashrrev_i32_e32 v77, 31, v76
	v_or_b32_e32 v40, 16, v76
	v_lshl_or_b32 v83, v35, 9, v36
	v_lshlrev_b64 v[36:37], 13, v[76:77]
	v_ashrrev_i32_e32 v41, 31, v40
	v_lshl_add_u64 v[36:37], s[4:5], 0, v[36:37]
	v_lshlrev_b64 v[40:41], 13, v[40:41]
	v_lshl_add_u64 v[78:79], v[36:37], 0, v[182:183]
	v_lshl_add_u64 v[40:41], s[4:5], 0, v[40:41]
	v_lshlrev_b32_e32 v35, 4, v196
	s_barrier
	global_load_dwordx4 v[36:39], v[78:79], off
	v_lshl_add_u64 v[52:53], v[40:41], 0, v[182:183]
	v_mad_i64_i32 v[44:45], s[4:5], v82, s61, v[80:81]
	v_and_b32_e32 v184, 0x70, v35
	global_load_dwordx4 v[40:43], v[52:53], off
	v_lshl_add_u64 v[44:45], v[44:45], 0, v[184:185]
	global_load_dwordx4 v[44:47], v[44:45], off offset:3072
	s_nop 0
	global_load_dwordx4 v[48:51], v[78:79], off offset:256
	s_nop 0
	global_load_dwordx4 v[52:55], v[52:53], off offset:256
	s_mov_b32 s4, 0x80000
	v_add_co_u32_e32 v56, vcc, s4, v78
	s_mov_b64 s[4:5], 0xa0000
	s_nop 0
	v_addc_co_u32_e32 v57, vcc, 0, v79, vcc
	v_lshl_add_u64 v[72:73], v[78:79], 0, s[4:5]
	s_mov_b32 s4, 0xa0000
	v_add_co_u32_e32 v60, vcc, s4, v78
	v_mad_i64_i32 v[64:65], s[4:5], v64, s61, v[80:81]
	v_mul_lo_u32 v198, v76, s67
	v_lshl_add_u64 v[68:69], v[78:79], 0, s[40:41]
	v_addc_co_u32_e32 v61, vcc, 0, v79, vcc
	v_lshl_add_u64 v[64:65], v[64:65], 0, v[184:185]
	v_add3_u32 v76, 16, v198, v182
	s_mov_b64 s[4:5], 0x100000
	global_load_dwordx4 v[56:59], v[56:57], off
	v_mul_lo_u32 v199, v82, s67
	global_load_dwordx4 v[60:63], v[60:61], off
	s_nop 0
	global_load_dwordx4 v[64:67], v[64:65], off offset:3072
	s_nop 0
	global_load_dwordx4 v[68:71], v[68:69], off offset:256
	s_nop 0
	global_load_dwordx4 v[72:75], v[72:73], off offset:256
	s_waitcnt vmcnt(9)
	ds_write_b128 v76, v[36:39]
	s_waitcnt vmcnt(8)
	ds_write_b128 v76, v[40:43] offset:6400
	v_add_u32_e32 v43, 16, v83
	v_lshl_add_u64 v[36:37], v[78:79], 0, s[4:5]
	s_mov_b32 s4, 0x100000
	v_add3_u32 v42, 16, v199, v184
	v_add_u32_e32 v200, 0x12c00, v43
	v_add_co_u32_e32 v38, vcc, s4, v78
	s_waitcnt vmcnt(7)
	ds_write_b128 v42, v[44:47] offset:256
	s_waitcnt vmcnt(6)
	ds_write_b128 v200, v[48:51]
	s_waitcnt vmcnt(5)
	ds_write_b128 v200, v[52:55] offset:4096
	v_addc_co_u32_e32 v39, vcc, 0, v79, vcc
	s_mov_b64 s[4:5], 0x120000
	global_load_dwordx4 v[128:131], v[38:39], off
	v_lshl_add_u64 v[38:39], v[78:79], 0, s[4:5]
	s_mov_b32 s4, 0x120000
	v_add_co_u32_e32 v40, vcc, s4, v78
	s_nop 1
	v_addc_co_u32_e32 v41, vcc, 0, v79, vcc
	global_load_dwordx4 v[132:135], v[40:41], off
	v_add_u32_e32 v40, 0x80, v82
	v_mad_i64_i32 v[40:41], s[4:5], v40, s61, v[80:81]
	v_lshl_add_u64 v[40:41], v[40:41], 0, v[184:185]
	global_load_dwordx4 v[136:139], v[40:41], off offset:3072
	global_load_dwordx4 v[140:143], v[36:37], off offset:256
	global_load_dwordx4 v[144:147], v[38:39], off offset:256
	v_add_u32_e32 v36, 0x16c00, v43
	s_waitcnt vmcnt(9)
	ds_write_b128 v76, v[56:59] offset:25600
	s_waitcnt vmcnt(8)
	ds_write_b128 v76, v[60:63] offset:32000
	s_waitcnt vmcnt(7)
	ds_write_b128 v42, v[64:67] offset:25856
	s_waitcnt vmcnt(6)
	ds_write_b128 v36, v[68:71]
	s_waitcnt vmcnt(5)
	ds_write_b128 v36, v[72:75] offset:4096
	s_waitcnt lgkmcnt(0)
	s_barrier
	s_cbranch_scc1 .LBB0_1285
	s_barrier
	s_setprio 1

; #define PV(VB) do { PV_D0(VB, 0); PV_D0(VB, 1); PV_D0(VB, 2); PV_D0(VB, 3); } while (0)
; template <int DK, bool KBIAS, int ROPE>
; __device__ __forceinline__ void attn_pp(const AttnArgs& a) {
;     ...
;   for (int t = 0; t < NT; ++t) {
;     __builtin_amdgcn_s_setprio(1);
;     QKT(ks);
;     if (t > 0) PV((vs + 3) & 3);
.LBB0_1286:
	s_mul_i32 s84, s80, 0x6400
	v_add_u32_e32 v238, s84, v202
	ds_read_b128 v[64:67], v238 offset:0
	ds_read_b128 v[68:71], v238 offset:0x3200
	ds_read_b128 v[206:209], v238 offset:32
	ds_read_b128 v[210:213], v238 offset:0x3220
	ds_read_b128 v[214:217], v238 offset:64
	ds_read_b128 v[218:221], v238 offset:0x3240
	ds_read_b128 v[222:225], v238 offset:0x60
	ds_read_b128 v[226:229], v238 offset:0x3260
	s_waitcnt lgkmcnt(4)
	s_nop 0
	v_mfma_f32_32x32x16_bf16 v[80:95], v[64:67], v[96:99], 0
	v_mfma_f32_32x32x16_bf16 v[64:79], v[68:71], v[96:99], 0
	v_mfma_f32_32x32x16_bf16 v[80:95], v[206:209], v[100:103], v[80:95]
	ds_read_b128 v[206:209], v238 offset:0x80
	v_mfma_f32_32x32x16_bf16 v[64:79], v[210:213], v[100:103], v[64:79]
	ds_read_b128 v[210:213], v238 offset:0x3280
	ds_read_b128 v[230:233], v238 offset:0xa0
	ds_read_b128 v[234:237], v238 offset:0x32a0
	s_waitcnt lgkmcnt(4)
	v_mfma_f32_32x32x16_bf16 v[80:95], v[214:217], v[104:107], v[80:95]
	ds_read_b128 v[214:217], v238 offset:0xc0
	v_mfma_f32_32x32x16_bf16 v[64:79], v[218:221], v[104:107], v[64:79]
	ds_read_b128 v[218:221], v238 offset:0x32c0
	v_mfma_f32_32x32x16_bf16 v[80:95], v[222:225], v[108:111], v[80:95]
	ds_read_b128 v[222:225], v238 offset:0xe0
	v_mfma_f32_32x32x16_bf16 v[64:79], v[226:229], v[108:111], v[64:79]
	ds_read_b128 v[226:229], v238 offset:0x32e0
	s_waitcnt lgkmcnt(4)
	v_mfma_f32_32x32x16_bf16 v[80:95], v[206:209], v[112:115], v[80:95]
	ds_read_b128 v[206:209], v238 offset:0x100
	v_mfma_f32_32x32x16_bf16 v[64:79], v[210:213], v[112:115], v[64:79]
	ds_read_b128 v[210:213], v238 offset:0x3300
	v_mfma_f32_32x32x16_bf16 v[80:95], v[230:233], v[116:119], v[80:95]
	ds_read_b128 v[230:233], v238 offset:0x120
	v_mfma_f32_32x32x16_bf16 v[64:79], v[234:237], v[116:119], v[64:79]
	ds_read_b128 v[234:237], v238 offset:0x3320
	s_waitcnt lgkmcnt(4)
	v_mfma_f32_32x32x16_bf16 v[80:95], v[214:217], v[120:123], v[80:95]
	ds_read_b128 v[214:217], v238 offset:0x140
	v_mfma_f32_32x32x16_bf16 v[64:79], v[218:221], v[120:123], v[64:79]
	ds_read_b128 v[218:221], v238 offset:0x3340
	v_mfma_f32_32x32x16_bf16 v[80:95], v[222:225], v[124:127], v[80:95]
	ds_read_b128 v[222:225], v238 offset:0x160
	v_mfma_f32_32x32x16_bf16 v[64:79], v[226:229], v[124:127], v[64:79]
	ds_read_b128 v[226:229], v238 offset:0x3360
	s_waitcnt lgkmcnt(4)
	v_mfma_f32_32x32x16_bf16 v[80:95], v[206:209], v[148:151], v[80:95]
	s_waitcnt lgkmcnt(0)
	v_mfma_f32_32x32x16_bf16 v[64:79], v[210:213], v[148:151], v[64:79]
	v_mfma_f32_32x32x16_bf16 v[80:95], v[230:233], v[152:155], v[80:95]
	v_mfma_f32_32x32x16_bf16 v[64:79], v[234:237], v[152:155], v[64:79]
	v_mfma_f32_32x32x16_bf16 v[80:95], v[214:217], v[156:159], v[80:95]
	s_cmp_eq_u32 s38, 63
	v_mfma_f32_32x32x16_bf16 v[64:79], v[218:221], v[156:159], v[64:79]
	v_mfma_f32_32x32x16_bf16 v[80:95], v[222:225], v[160:163], v[80:95]
	v_mfma_f32_32x32x16_bf16 v[64:79], v[226:229], v[160:163], v[64:79]
	s_cbranch_scc1 .LBB0_1288
	s_lshl_b32 s34, s82, 14
	s_add_i32 s34, s34, 0xc000
	s_and_b32 s34, s34, 0xc000
	v_add_u32_e32 v230, s34, v201
	ds_read_b64_tr_b16 v[206:207], v230 offset:0
	ds_read_b64_tr_b16 v[208:209], v230 offset:0x800
	ds_read_b64_tr_b16 v[210:211], v230 offset:0x200
	ds_read_b64_tr_b16 v[212:213], v230 offset:0xa00
	ds_read_b64_tr_b16 v[214:215], v230 offset:0x400
	ds_read_b64_tr_b16 v[216:217], v230 offset:0xc00
	ds_read_b64_tr_b16 v[218:219], v230 offset:0x600
	ds_read_b64_tr_b16 v[220:221], v230 offset:0xe00
	ds_read_b64_tr_b16 v[222:223], v230 offset:0x1000
	ds_read_b64_tr_b16 v[224:225], v230 offset:0x1800
	ds_read_b64_tr_b16 v[226:227], v230 offset:0x1200
	ds_read_b64_tr_b16 v[228:229], v230 offset:0x1a00
	s_waitcnt lgkmcnt(8)
	s_nop 0
	v_mfma_f32_32x32x16_bf16 v[48:63], v[176:179], v[206:209], v[48:63]
	ds_read_b64_tr_b16 v[206:207], v230 offset:0x1400
	ds_read_b64_tr_b16 v[208:209], v230 offset:0x1c00
	v_mfma_f32_32x32x16_bf16 v[32:47], v[176:179], v[210:213], v[32:47]
	ds_read_b64_tr_b16 v[210:211], v230 offset:0x1600
	ds_read_b64_tr_b16 v[212:213], v230 offset:0x1e00
	s_waitcnt lgkmcnt(8)
	v_mfma_f32_32x32x16_bf16 v[16:31], v[176:179], v[214:217], v[16:31]
	v_mfma_f32_32x32x16_bf16 v[0:15], v[176:179], v[218:221], v[0:15]
	ds_read_b64_tr_b16 v[176:177], v230 offset:0x2000
	ds_read_b64_tr_b16 v[178:179], v230 offset:0x2800
	ds_read_b64_tr_b16 v[214:215], v230 offset:0x2200
	ds_read_b64_tr_b16 v[216:217], v230 offset:0x2a00
	s_waitcnt lgkmcnt(8)
	v_mfma_f32_32x32x16_bf16 v[48:63], v[172:175], v[222:225], v[48:63]
	ds_read_b64_tr_b16 v[218:219], v230 offset:0x2400
	ds_read_b64_tr_b16 v[220:221], v230 offset:0x2c00
	ds_read_b64_tr_b16 v[222:223], v230 offset:0x2600
	ds_read_b64_tr_b16 v[224:225], v230 offset:0x2e00
	s_waitcnt lgkmcnt(8)
	v_mfma_f32_32x32x16_bf16 v[32:47], v[172:175], v[226:229], v[32:47]
	v_mfma_f32_32x32x16_bf16 v[16:31], v[172:175], v[206:209], v[16:31]
	v_mfma_f32_32x32x16_bf16 v[0:15], v[172:175], v[210:213], v[0:15]
	ds_read_b64_tr_b16 v[172:173], v230 offset:0x3000
	ds_read_b64_tr_b16 v[174:175], v230 offset:0x3800
	ds_read_b64_tr_b16 v[206:207], v230 offset:0x3200
	ds_read_b64_tr_b16 v[208:209], v230 offset:0x3a00
	s_waitcnt lgkmcnt(8)
	v_mfma_f32_32x32x16_bf16 v[48:63], v[168:171], v[176:179], v[48:63]
	ds_read_b64_tr_b16 v[176:177], v230 offset:0x3400
	ds_read_b64_tr_b16 v[178:179], v230 offset:0x3c00
	ds_read_b64_tr_b16 v[210:211], v230 offset:0x3600
	ds_read_b64_tr_b16 v[212:213], v230 offset:0x3e00
	s_waitcnt lgkmcnt(8)
	v_mfma_f32_32x32x16_bf16 v[32:47], v[168:171], v[214:217], v[32:47]
	v_mfma_f32_32x32x16_bf16 v[16:31], v[168:171], v[218:221], v[16:31]
	s_waitcnt lgkmcnt(4)
	v_mfma_f32_32x32x16_bf16 v[0:15], v[168:171], v[222:225], v[0:15]
	v_mfma_f32_32x32x16_bf16 v[48:63], v[164:167], v[172:175], v[48:63]
	s_waitcnt lgkmcnt(0)
	v_mfma_f32_32x32x16_bf16 v[32:47], v[164:167], v[206:209], v[32:47]
	v_mfma_f32_32x32x16_bf16 v[16:31], v[164:167], v[176:179], v[16:31]
	v_mfma_f32_32x32x16_bf16 v[0:15], v[164:167], v[210:213], v[0:15]
; template <int DK, bool KBIAS, int ROPE>
; __device__ __forceinline__ void attn_pp(const AttnArgs& a) {
;     ...
;     __builtin_amdgcn_s_setprio(0);
;     __syncthreads();
;     SOFTMAX(t, vs);
.LBB0_1288:
	s_cmp_le_i32 s38, s75
	s_barrier
	s_cbranch_scc1 .LBB0_1290
	v_add_u32_e32 v164, s38, v183
	v_subrev_u32_e32 v166, 31, v164
	v_subrev_u32_e32 v165, 63, v164
	v_cmp_le_i32_e32 vcc, v166, v197
	s_nop 2
	v_cndmask_b32_e32 v64, v192, v64, vcc
	v_cmp_lt_i32_e32 vcc, v165, v197
	s_nop 1
	v_cndmask_b32_e32 v81, v192, v81, vcc
	v_cmp_le_i32_e32 vcc, v165, v197
	v_subrev_u32_e32 v165, 30, v164
	s_nop 0
	v_cndmask_b32_e32 v80, v192, v80, vcc
	v_cmp_le_i32_e32 vcc, v165, v197
	v_subrev_u32_e32 v165, 61, v164
	s_nop 0
	v_cndmask_b32_e32 v65, v192, v65, vcc
	v_cmp_le_i32_e32 vcc, v165, v197
	v_subrev_u32_e32 v165, 29, v164
	s_nop 0
	v_cndmask_b32_e32 v82, v192, v82, vcc
	v_cmp_le_i32_e32 vcc, v165, v197
	v_subrev_u32_e32 v165, 60, v164
	s_nop 0
	v_cndmask_b32_e32 v66, v192, v66, vcc
	v_cmp_le_i32_e32 vcc, v165, v197
	v_subrev_u32_e32 v165, 28, v164
	s_nop 0
	v_cndmask_b32_e32 v83, v192, v83, vcc
	v_cmp_le_i32_e32 vcc, v165, v197
	v_subrev_u32_e32 v165, 55, v164
	s_nop 0
	v_cndmask_b32_e32 v67, v192, v67, vcc
	v_cmp_le_i32_e32 vcc, v165, v197
	v_subrev_u32_e32 v165, 23, v164
	s_nop 0
	v_cndmask_b32_e32 v84, v192, v84, vcc
	v_cmp_le_i32_e32 vcc, v165, v197
	v_subrev_u32_e32 v165, 54, v164
	s_nop 0
	v_cndmask_b32_e32 v68, v192, v68, vcc
	v_cmp_le_i32_e32 vcc, v165, v197
	v_subrev_u32_e32 v165, 22, v164
	s_nop 0
	v_cndmask_b32_e32 v85, v192, v85, vcc
	v_cmp_le_i32_e32 vcc, v165, v197
	v_subrev_u32_e32 v165, 53, v164
	s_nop 0
	v_cndmask_b32_e32 v69, v192, v69, vcc
	v_cmp_le_i32_e32 vcc, v165, v197
	v_subrev_u32_e32 v165, 21, v164
	s_nop 0
	v_cndmask_b32_e32 v86, v192, v86, vcc
	v_cmp_le_i32_e32 vcc, v165, v197
	v_subrev_u32_e32 v165, 52, v164
	s_nop 0
	v_cndmask_b32_e32 v70, v192, v70, vcc
	v_cmp_le_i32_e32 vcc, v165, v197
	v_subrev_u32_e32 v165, 20, v164
	s_nop 0
	v_cndmask_b32_e32 v87, v192, v87, vcc
	v_cmp_le_i32_e32 vcc, v165, v197
	v_subrev_u32_e32 v165, 47, v164
	s_nop 0
	v_cndmask_b32_e32 v71, v192, v71, vcc
	v_cmp_le_i32_e32 vcc, v165, v197
	v_add_u32_e32 v165, -15, v164
	s_nop 0
	v_cndmask_b32_e32 v88, v192, v88, vcc
	v_cmp_le_i32_e32 vcc, v165, v197
	v_subrev_u32_e32 v165, 46, v164
	s_nop 0
	v_cndmask_b32_e32 v72, v192, v72, vcc
	v_cmp_le_i32_e32 vcc, v165, v197
	v_add_u32_e32 v165, -14, v164
	s_nop 0
	v_cndmask_b32_e32 v89, v192, v89, vcc
	v_cmp_le_i32_e32 vcc, v165, v197
	v_subrev_u32_e32 v165, 45, v164
	s_nop 0
	v_cndmask_b32_e32 v73, v192, v73, vcc
	v_cmp_le_i32_e32 vcc, v165, v197
	v_add_u32_e32 v165, -13, v164
	s_nop 0
	v_cndmask_b32_e32 v90, v192, v90, vcc
	v_cmp_le_i32_e32 vcc, v165, v197
	v_subrev_u32_e32 v165, 44, v164
	s_nop 0
	v_cndmask_b32_e32 v74, v192, v74, vcc
	v_cmp_le_i32_e32 vcc, v165, v197
	v_add_u32_e32 v165, -12, v164
	s_nop 0
	v_cndmask_b32_e32 v91, v192, v91, vcc
	v_cmp_le_i32_e32 vcc, v165, v197
	v_subrev_u32_e32 v165, 39, v164
	s_nop 0
	v_cndmask_b32_e32 v75, v192, v75, vcc
	v_cmp_le_i32_e32 vcc, v165, v197
	v_add_u32_e32 v165, -7, v164
	s_nop 0
	v_cndmask_b32_e32 v92, v192, v92, vcc
	v_cmp_le_i32_e32 vcc, v165, v197
	v_subrev_u32_e32 v165, 38, v164
	s_nop 0
	v_cndmask_b32_e32 v76, v192, v76, vcc
	v_cmp_le_i32_e32 vcc, v165, v197
	v_add_u32_e32 v165, -6, v164
	s_nop 0
	v_cndmask_b32_e32 v93, v192, v93, vcc
	v_cmp_le_i32_e32 vcc, v165, v197
	v_subrev_u32_e32 v165, 37, v164
	s_nop 0
	v_cndmask_b32_e32 v77, v192, v77, vcc
	v_cmp_le_i32_e32 vcc, v165, v197
	v_add_u32_e32 v165, -5, v164
	s_nop 0
	v_cndmask_b32_e32 v94, v192, v94, vcc
	v_cmp_le_i32_e32 vcc, v165, v197
	v_subrev_u32_e32 v165, 36, v164
	v_add_u32_e32 v164, -4, v164
	v_cndmask_b32_e32 v78, v192, v78, vcc
	v_cmp_le_i32_e32 vcc, v165, v197
	s_nop 1
	v_cndmask_b32_e32 v95, v192, v95, vcc
	v_cmp_le_i32_e32 vcc, v164, v197
	s_nop 1
	v_cndmask_b32_e32 v79, v192, v79, vcc

; #define PV(VB) do { PV_D0(VB, 0); PV_D0(VB, 1); PV_D0(VB, 2); PV_D0(VB, 3); } while (0)
; template <int DK, bool KBIAS, int ROPE>
; __device__ __forceinline__ void attn_pp(const AttnArgs& a) {
;     ...
;   PV((vs + 3) & 3);
;   if (grp == 0) __syncthreads();
.LBB0_1299:
	s_setprio 0
	s_lshl_b32 s34, s82, 14
	s_add_i32 s34, s34, 0xc000
	s_and_b32 s34, s34, 0xc000
	v_add_u32_e32 v64, s34, v201
	ds_read_b64_tr_b16 v[66:67], v64 offset:0
	ds_read_b64_tr_b16 v[68:69], v64 offset:0x800
	ds_read_b64_tr_b16 v[70:71], v64 offset:0x200
	ds_read_b64_tr_b16 v[72:73], v64 offset:0xa00
	ds_read_b64_tr_b16 v[74:75], v64 offset:0x400
	ds_read_b64_tr_b16 v[76:77], v64 offset:0xc00
	ds_read_b64_tr_b16 v[78:79], v64 offset:0x600
	ds_read_b64_tr_b16 v[80:81], v64 offset:0xe00
	ds_read_b64_tr_b16 v[82:83], v64 offset:0x1000
	ds_read_b64_tr_b16 v[84:85], v64 offset:0x1800
	ds_read_b64_tr_b16 v[86:87], v64 offset:0x1200
	ds_read_b64_tr_b16 v[88:89], v64 offset:0x1a00
	s_waitcnt lgkmcnt(8)
	s_nop 0
	v_mfma_f32_32x32x16_bf16 v[48:63], v[176:179], v[66:69], v[48:63]
	ds_read_b64_tr_b16 v[66:67], v64 offset:0x1400
	ds_read_b64_tr_b16 v[68:69], v64 offset:0x1c00
	v_mfma_f32_32x32x16_bf16 v[32:47], v[176:179], v[70:73], v[32:47]
	ds_read_b64_tr_b16 v[70:71], v64 offset:0x1600
	ds_read_b64_tr_b16 v[72:73], v64 offset:0x1e00
	s_waitcnt lgkmcnt(8)
	v_mfma_f32_32x32x16_bf16 v[16:31], v[176:179], v[74:77], v[16:31]
	ds_read_b64_tr_b16 v[74:75], v64 offset:0x2000
	ds_read_b64_tr_b16 v[76:77], v64 offset:0x2800
	v_mfma_f32_32x32x16_bf16 v[0:15], v[176:179], v[78:81], v[0:15]
	ds_read_b64_tr_b16 v[78:79], v64 offset:0x2200
	ds_read_b64_tr_b16 v[80:81], v64 offset:0x2a00
	s_waitcnt lgkmcnt(8)
	v_mfma_f32_32x32x16_bf16 v[48:63], v[172:175], v[82:85], v[48:63]
	ds_read_b64_tr_b16 v[82:83], v64 offset:0x2400
	ds_read_b64_tr_b16 v[84:85], v64 offset:0x2c00
	v_mfma_f32_32x32x16_bf16 v[32:47], v[172:175], v[86:89], v[32:47]
	ds_read_b64_tr_b16 v[86:87], v64 offset:0x2600
	ds_read_b64_tr_b16 v[88:89], v64 offset:0x2e00
	s_waitcnt lgkmcnt(8)
	v_mfma_f32_32x32x16_bf16 v[16:31], v[172:175], v[66:69], v[16:31]
	ds_read_b64_tr_b16 v[66:67], v64 offset:0x3000
	ds_read_b64_tr_b16 v[68:69], v64 offset:0x3800
	v_mfma_f32_32x32x16_bf16 v[0:15], v[172:175], v[70:73], v[0:15]
	ds_read_b64_tr_b16 v[70:71], v64 offset:0x3200
	ds_read_b64_tr_b16 v[72:73], v64 offset:0x3a00
	s_waitcnt lgkmcnt(8)
	v_mfma_f32_32x32x16_bf16 v[48:63], v[168:171], v[74:77], v[48:63]
	ds_read_b64_tr_b16 v[74:75], v64 offset:0x3400
	ds_read_b64_tr_b16 v[76:77], v64 offset:0x3c00
	v_mfma_f32_32x32x16_bf16 v[32:47], v[168:171], v[78:81], v[32:47]
	ds_read_b64_tr_b16 v[78:79], v64 offset:0x3600
	ds_read_b64_tr_b16 v[80:81], v64 offset:0x3e00
	s_waitcnt lgkmcnt(8)
	v_mfma_f32_32x32x16_bf16 v[16:31], v[168:171], v[82:85], v[16:31]
	s_waitcnt lgkmcnt(4)
	v_mfma_f32_32x32x16_bf16 v[0:15], v[168:171], v[86:89], v[0:15]
	v_mfma_f32_32x32x16_bf16 v[48:63], v[164:167], v[66:69], v[48:63]
	s_waitcnt lgkmcnt(0)
	v_mfma_f32_32x32x16_bf16 v[32:47], v[164:167], v[70:73], v[32:47]
	v_mfma_f32_32x32x16_bf16 v[16:31], v[164:167], v[74:77], v[16:31]
	s_cmpk_lt_u32 s77, 0x100
	v_mfma_f32_32x32x16_bf16 v[0:15], v[164:167], v[78:81], v[0:15]
	s_cbranch_scc0 .LBB0_1301
	s_barrier

; template <int DK, bool KBIAS, int ROPE>
; __device__ __forceinline__ void attn_pp(const AttnArgs& a) {
;     ...
;   __syncthreads();
;   LOADT(0); LOADT_B(1); WRITET(0, 0); LOADT(2); WRITET_B(1, 1);
;   __syncthreads();
;   if (grp == 1) __syncthreads();
.LBB0_2067:
	s_or_b64 exec, exec, s[6:7]
	s_waitcnt vmcnt(7)
	ds_write_b128 v36, v[0:3] offset:17408
	s_waitcnt vmcnt(6)
	ds_write_b128 v36, v[4:7] offset:21760
	v_add_u32_e32 v0, 0x10c00, v177
	s_waitcnt vmcnt(5)
	ds_write_b128 v0, v[8:11]
	s_waitcnt vmcnt(4)
	ds_write_b128 v0, v[12:15] offset:4096
	s_and_saveexec_b64 s[6:7], s[8:9]
	s_add_i32 s18, 16, 0x1cc00
	v_lshl_add_u32 v0, v162, 2, s18
	ds_write_b32 v0, v34 offset:256
	s_or_b64 exec, exec, s[6:7]
	s_cmp_lg_u32 s15, 1
	s_waitcnt lgkmcnt(0)
	s_barrier
	s_cbranch_scc1 .LBB0_2071
	s_barrier
	s_setprio 1

; #define PV(VB) do { PV_D0(VB, 0); PV_D0(VB, 1); PV_D0(VB, 2); PV_D0(VB, 3); } while (0)
; template <int DK, bool KBIAS, int ROPE>
; __device__ __forceinline__ void attn_pp(const AttnArgs& a) {
;     ...
;   for (int t = 0; t < NT; ++t) {
;     __builtin_amdgcn_s_setprio(1);
;     QKT(ks);
;     if (t > 0) PV((vs + 3) & 3);
.LBB0_2072:
	s_mul_i32 s51, s50, 0x4400
	v_add_u32_e32 v195, s51, v180
	ds_read_b128 v[64:67], v195 offset:0
	ds_read_b128 v[68:71], v195 offset:0x2200
	ds_read_b128 v[186:189], v195 offset:32
	ds_read_b128 v[190:193], v195 offset:0x2220
	ds_read_b128 v[196:199], v195 offset:64
	ds_read_b128 v[200:203], v195 offset:0x2240
	ds_read_b128 v[204:207], v195 offset:0x60
	ds_read_b128 v[208:211], v195 offset:0x2260
	ds_read_b128 v[212:215], v195 offset:0x80
	ds_read_b128 v[216:219], v195 offset:0x2280
	ds_read_b128 v[220:223], v195 offset:0xa0
	ds_read_b128 v[224:227], v195 offset:0x22a0
	s_waitcnt lgkmcnt(8)
	s_nop 0
	v_mfma_f32_32x32x16_bf16 v[80:95], v[64:67], v[96:99], 0
	v_mfma_f32_32x32x16_bf16 v[64:79], v[68:71], v[96:99], 0
	v_mfma_f32_32x32x16_bf16 v[80:95], v[186:189], v[100:103], v[80:95]
	ds_read_b128 v[186:189], v195 offset:0xc0
	ds_read_b128 v[228:231], v195 offset:0x22c0
	ds_read_b128 v[232:235], v195 offset:0xe0
	ds_read_b128 v[236:239], v195 offset:0x22e0
	s_waitcnt lgkmcnt(8)
	v_mfma_f32_32x32x16_bf16 v[64:79], v[190:193], v[100:103], v[64:79]
	v_mfma_f32_32x32x16_bf16 v[80:95], v[196:199], v[104:107], v[80:95]
	s_waitcnt lgkmcnt(4)
	v_mfma_f32_32x32x16_bf16 v[64:79], v[200:203], v[104:107], v[64:79]
	v_mfma_f32_32x32x16_bf16 v[80:95], v[204:207], v[108:111], v[80:95]
	v_mfma_f32_32x32x16_bf16 v[64:79], v[208:211], v[108:111], v[64:79]
	v_mfma_f32_32x32x16_bf16 v[80:95], v[212:215], v[112:115], v[80:95]
	s_waitcnt lgkmcnt(0)
	v_mfma_f32_32x32x16_bf16 v[64:79], v[216:219], v[112:115], v[64:79]
	v_mfma_f32_32x32x16_bf16 v[80:95], v[220:223], v[116:119], v[80:95]
	v_mfma_f32_32x32x16_bf16 v[64:79], v[224:227], v[116:119], v[64:79]
	v_mfma_f32_32x32x16_bf16 v[80:95], v[186:189], v[120:123], v[80:95]
	s_cmp_eq_u32 s41, 0
	v_mfma_f32_32x32x16_bf16 v[64:79], v[228:231], v[120:123], v[64:79]
	v_mfma_f32_32x32x16_bf16 v[80:95], v[232:235], v[124:127], v[80:95]
	v_mfma_f32_32x32x16_bf16 v[64:79], v[236:239], v[124:127], v[64:79]
	s_cbranch_scc1 .LBB0_2074
	s_lshl_b32 s20, s49, 14
	s_add_i32 s20, s20, 0xc000
	s_and_b32 s20, s20, 0xc000
	v_add_u32_e32 v195, s20, v178
	ds_read_b64_tr_b16 v[186:187], v195 offset:0
	ds_read_b64_tr_b16 v[188:189], v195 offset:0x800
	ds_read_b64_tr_b16 v[190:191], v195 offset:0x200
	ds_read_b64_tr_b16 v[192:193], v195 offset:0xa00
	ds_read_b64_tr_b16 v[196:197], v195 offset:0x400
	ds_read_b64_tr_b16 v[198:199], v195 offset:0xc00
	ds_read_b64_tr_b16 v[200:201], v195 offset:0x600
	ds_read_b64_tr_b16 v[202:203], v195 offset:0xe00
	ds_read_b64_tr_b16 v[204:205], v195 offset:0x1000
	ds_read_b64_tr_b16 v[206:207], v195 offset:0x1800
	ds_read_b64_tr_b16 v[208:209], v195 offset:0x1200
	ds_read_b64_tr_b16 v[210:211], v195 offset:0x1a00
	s_waitcnt lgkmcnt(8)
	s_nop 0
	v_mfma_f32_32x32x16_bf16 v[48:63], v[156:159], v[186:189], v[48:63]
	ds_read_b64_tr_b16 v[186:187], v195 offset:0x1400
	ds_read_b64_tr_b16 v[188:189], v195 offset:0x1c00
	ds_read_b64_tr_b16 v[212:213], v195 offset:0x1600
	ds_read_b64_tr_b16 v[214:215], v195 offset:0x1e00
	s_waitcnt lgkmcnt(8)
	v_mfma_f32_32x32x16_bf16 v[32:47], v[156:159], v[190:193], v[32:47]
	v_mfma_f32_32x32x16_bf16 v[16:31], v[156:159], v[196:199], v[16:31]
	ds_read_b64_tr_b16 v[190:191], v195 offset:0x2000
	ds_read_b64_tr_b16 v[192:193], v195 offset:0x2800
	ds_read_b64_tr_b16 v[196:197], v195 offset:0x2200
	ds_read_b64_tr_b16 v[198:199], v195 offset:0x2a00
	s_waitcnt lgkmcnt(8)
	v_mfma_f32_32x32x16_bf16 v[0:15], v[156:159], v[200:203], v[0:15]
	v_mfma_f32_32x32x16_bf16 v[48:63], v[152:155], v[204:207], v[48:63]
	ds_read_b64_tr_b16 v[156:157], v195 offset:0x2400
	ds_read_b64_tr_b16 v[158:159], v195 offset:0x2c00
	ds_read_b64_tr_b16 v[200:201], v195 offset:0x2600
	ds_read_b64_tr_b16 v[202:203], v195 offset:0x2e00
	s_waitcnt lgkmcnt(8)
	v_mfma_f32_32x32x16_bf16 v[32:47], v[152:155], v[208:211], v[32:47]
	v_mfma_f32_32x32x16_bf16 v[16:31], v[152:155], v[186:189], v[16:31]
	ds_read_b64_tr_b16 v[186:187], v195 offset:0x3000
	ds_read_b64_tr_b16 v[188:189], v195 offset:0x3800
	ds_read_b64_tr_b16 v[204:205], v195 offset:0x3200
	ds_read_b64_tr_b16 v[206:207], v195 offset:0x3a00
	s_waitcnt lgkmcnt(8)
	v_mfma_f32_32x32x16_bf16 v[0:15], v[152:155], v[212:215], v[0:15]
	v_mfma_f32_32x32x16_bf16 v[48:63], v[148:151], v[190:193], v[48:63]
	ds_read_b64_tr_b16 v[152:153], v195 offset:0x3400
	ds_read_b64_tr_b16 v[154:155], v195 offset:0x3c00
	ds_read_b64_tr_b16 v[190:191], v195 offset:0x3600
	ds_read_b64_tr_b16 v[192:193], v195 offset:0x3e00
	s_waitcnt lgkmcnt(8)
	v_mfma_f32_32x32x16_bf16 v[32:47], v[148:151], v[196:199], v[32:47]
	v_mfma_f32_32x32x16_bf16 v[16:31], v[148:151], v[156:159], v[16:31]
	s_waitcnt lgkmcnt(4)
	v_mfma_f32_32x32x16_bf16 v[0:15], v[148:151], v[200:203], v[0:15]
	v_mfma_f32_32x32x16_bf16 v[48:63], v[144:147], v[186:189], v[48:63]
	s_waitcnt lgkmcnt(0)
	v_mfma_f32_32x32x16_bf16 v[32:47], v[144:147], v[204:207], v[32:47]
	v_mfma_f32_32x32x16_bf16 v[16:31], v[144:147], v[152:155], v[16:31]
	v_mfma_f32_32x32x16_bf16 v[0:15], v[144:147], v[190:193], v[0:15]
; template <int DK, bool KBIAS, int ROPE>
; __device__ __forceinline__ void attn_pp(const AttnArgs& a) {
;     ...
;     __builtin_amdgcn_s_setprio(0);
;     __syncthreads();
;     SOFTMAX(t, vs);
.LBB0_2074:
	v_lshl_add_u32 v190, s49, 8, v182
	s_barrier
	ds_read_b128 v[146:149], v190 offset:96
	ds_read_b128 v[150:153], v190 offset:64
	ds_read_b128 v[154:157], v190 offset:32
	ds_read_b128 v[186:189], v190
	s_waitcnt lgkmcnt(3)
	s_nop 1
	v_pk_fma_f32 v[94:95], v[94:95], s[2:3], v[148:149] op_sel_hi:[1,0,1]
	s_waitcnt lgkmcnt(2)
	v_pk_fma_f32 v[90:91], v[90:91], s[2:3], v[152:153] op_sel_hi:[1,0,1]
	s_waitcnt lgkmcnt(1)
	v_pk_fma_f32 v[86:87], v[86:87], s[2:3], v[156:157] op_sel_hi:[1,0,1]
	s_waitcnt lgkmcnt(0)
	v_pk_fma_f32 v[144:145], v[82:83], s[2:3], v[188:189] op_sel_hi:[1,0,1]
	v_pk_fma_f32 v[82:83], v[92:93], s[2:3], v[146:147] op_sel_hi:[1,0,1]
	v_pk_fma_f32 v[88:89], v[88:89], s[2:3], v[150:151] op_sel_hi:[1,0,1]
	ds_read_b128 v[146:149], v190 offset:192
	ds_read_b128 v[150:153], v190 offset:224
	ds_read_b128 v[156:159], v190 offset:128
	ds_read_b128 v[188:191], v190 offset:160
	s_add_i32 s20, s41, 63
	v_pk_fma_f32 v[84:85], v[84:85], s[2:3], v[154:155] op_sel_hi:[1,0,1]
	v_pk_fma_f32 v[80:81], v[80:81], s[2:3], v[186:187] op_sel_hi:[1,0,1]
	s_waitcnt lgkmcnt(2)
	v_pk_fma_f32 v[78:79], v[78:79], s[2:3], v[152:153] op_sel_hi:[1,0,1]
	v_pk_fma_f32 v[74:75], v[74:75], s[2:3], v[148:149] op_sel_hi:[1,0,1]
	s_waitcnt lgkmcnt(0)
	v_pk_fma_f32 v[70:71], v[70:71], s[2:3], v[190:191] op_sel_hi:[1,0,1]
	v_pk_fma_f32 v[92:93], v[66:67], s[2:3], v[158:159] op_sel_hi:[1,0,1]
	v_pk_fma_f32 v[66:67], v[76:77], s[2:3], v[150:151] op_sel_hi:[1,0,1]
	v_pk_fma_f32 v[72:73], v[72:73], s[2:3], v[146:147] op_sel_hi:[1,0,1]
	v_pk_fma_f32 v[68:69], v[68:69], s[2:3], v[188:189] op_sel_hi:[1,0,1]
	s_cmp_le_i32 s20, s33
	v_pk_fma_f32 v[64:65], v[64:65], s[2:3], v[156:157] op_sel_hi:[1,0,1]
	s_cbranch_scc1 .LBB0_2076
	v_add_u32_e32 v76, s41, v163
	v_add_u32_e32 v77, 32, v76
	v_cmp_le_i32_e32 vcc, v77, v174
	v_add_u32_e32 v77, 33, v76
	s_nop 0
	v_cndmask_b32_e32 v64, v171, v64, vcc
	v_cmp_lt_i32_e32 vcc, v76, v174
	s_nop 1
	v_cndmask_b32_e32 v81, v171, v81, vcc
	v_cmp_le_i32_e32 vcc, v76, v174
	s_nop 1
	v_cndmask_b32_e32 v80, v171, v80, vcc
	v_cmp_le_i32_e32 vcc, v77, v174
	v_add_u32_e32 v77, 2, v76
	s_nop 0
	v_cndmask_b32_e32 v65, v171, v65, vcc
	v_cmp_le_i32_e32 vcc, v77, v174
	v_add_u32_e32 v77, 34, v76
	s_nop 0
	v_cndmask_b32_e32 v144, v171, v144, vcc
	v_cmp_le_i32_e32 vcc, v77, v174
	v_add_u32_e32 v77, 3, v76
	s_nop 0
	v_cndmask_b32_e32 v92, v171, v92, vcc
	v_cmp_le_i32_e32 vcc, v77, v174
	v_add_u32_e32 v77, 35, v76
	s_nop 0
	v_cndmask_b32_e32 v145, v171, v145, vcc
	v_cmp_le_i32_e32 vcc, v77, v174
	v_add_u32_e32 v77, 8, v76
	s_nop 0
	v_cndmask_b32_e32 v93, v171, v93, vcc
	v_cmp_le_i32_e32 vcc, v77, v174
	v_add_u32_e32 v77, 40, v76
	s_nop 0
	v_cndmask_b32_e32 v84, v171, v84, vcc
	v_cmp_le_i32_e32 vcc, v77, v174
	v_add_u32_e32 v77, 9, v76
	s_nop 0
	v_cndmask_b32_e32 v68, v171, v68, vcc
	v_cmp_le_i32_e32 vcc, v77, v174
	v_add_u32_e32 v77, 41, v76
	s_nop 0
	v_cndmask_b32_e32 v85, v171, v85, vcc
	v_cmp_le_i32_e32 vcc, v77, v174
	v_add_u32_e32 v77, 10, v76
	s_nop 0
	v_cndmask_b32_e32 v69, v171, v69, vcc
	v_cmp_le_i32_e32 vcc, v77, v174
	v_add_u32_e32 v77, 42, v76
	s_nop 0
	v_cndmask_b32_e32 v86, v171, v86, vcc
	v_cmp_le_i32_e32 vcc, v77, v174
	v_add_u32_e32 v77, 11, v76
	s_nop 0
	v_cndmask_b32_e32 v70, v171, v70, vcc
	v_cmp_le_i32_e32 vcc, v77, v174
	v_add_u32_e32 v77, 43, v76
	s_nop 0
	v_cndmask_b32_e32 v87, v171, v87, vcc
	v_cmp_le_i32_e32 vcc, v77, v174
	v_add_u32_e32 v77, 16, v76
	s_nop 0
	v_cndmask_b32_e32 v71, v171, v71, vcc
	v_cmp_le_i32_e32 vcc, v77, v174
	v_add_u32_e32 v77, 48, v76
	s_nop 0
	v_cndmask_b32_e32 v88, v171, v88, vcc
	v_cmp_le_i32_e32 vcc, v77, v174
	v_add_u32_e32 v77, 17, v76
	s_nop 0
	v_cndmask_b32_e32 v72, v171, v72, vcc
	v_cmp_le_i32_e32 vcc, v77, v174
	v_add_u32_e32 v77, 49, v76
	s_nop 0
	v_cndmask_b32_e32 v89, v171, v89, vcc
	v_cmp_le_i32_e32 vcc, v77, v174
	v_add_u32_e32 v77, 18, v76
	s_nop 0
	v_cndmask_b32_e32 v73, v171, v73, vcc
	v_cmp_le_i32_e32 vcc, v77, v174
	v_add_u32_e32 v77, 50, v76
	s_nop 0
	v_cndmask_b32_e32 v90, v171, v90, vcc
	v_cmp_le_i32_e32 vcc, v77, v174
	v_add_u32_e32 v77, 19, v76
	s_nop 0
	v_cndmask_b32_e32 v74, v171, v74, vcc
	v_cmp_le_i32_e32 vcc, v77, v174
	v_add_u32_e32 v77, 51, v76
	s_nop 0
	v_cndmask_b32_e32 v91, v171, v91, vcc
	v_cmp_le_i32_e32 vcc, v77, v174
	v_add_u32_e32 v77, 24, v76
	s_nop 0
	v_cndmask_b32_e32 v75, v171, v75, vcc
	v_cmp_le_i32_e32 vcc, v77, v174
	v_add_u32_e32 v77, 56, v76
	s_nop 0
	v_cndmask_b32_e32 v82, v171, v82, vcc
	v_cmp_le_i32_e32 vcc, v77, v174
	v_add_u32_e32 v77, 25, v76
	s_nop 0
	v_cndmask_b32_e32 v66, v171, v66, vcc
	v_cmp_le_i32_e32 vcc, v77, v174
	v_add_u32_e32 v77, 57, v76
	s_nop 0
	v_cndmask_b32_e32 v83, v171, v83, vcc
	v_cmp_le_i32_e32 vcc, v77, v174
	v_add_u32_e32 v77, 26, v76
	s_nop 0
	v_cndmask_b32_e32 v67, v171, v67, vcc
	v_cmp_le_i32_e32 vcc, v77, v174
	v_add_u32_e32 v77, 58, v76
	s_nop 0
	v_cndmask_b32_e32 v94, v171, v94, vcc
	v_cmp_le_i32_e32 vcc, v77, v174
	v_add_u32_e32 v77, 27, v76
	v_add_u32_e32 v76, 59, v76
	v_cndmask_b32_e32 v78, v171, v78, vcc
	v_cmp_le_i32_e32 vcc, v77, v174
	s_nop 1
	v_cndmask_b32_e32 v95, v171, v95, vcc
	v_cmp_le_i32_e32 vcc, v76, v174
	s_nop 1
	v_cndmask_b32_e32 v79, v171, v79, vcc

; #define PV(VB) do { PV_D0(VB, 0); PV_D0(VB, 1); PV_D0(VB, 2); PV_D0(VB, 3); } while (0)
; template <int DK, bool KBIAS, int ROPE>
; __device__ __forceinline__ void attn_pp(const AttnArgs& a) {
;     ...
;   PV((vs + 3) & 3);
;   if (grp == 0) __syncthreads();
.LBB0_2089:
	s_setprio 0
	s_lshl_b32 s8, s49, 14
	s_add_i32 s8, s8, 0xc000
	s_and_b32 s8, s8, 0xc000
	v_add_u32_e32 v64, s8, v178
	ds_read_b64_tr_b16 v[66:67], v64 offset:0
	ds_read_b64_tr_b16 v[68:69], v64 offset:0x800
	ds_read_b64_tr_b16 v[70:71], v64 offset:0x200
	ds_read_b64_tr_b16 v[72:73], v64 offset:0xa00
	ds_read_b64_tr_b16 v[74:75], v64 offset:0x400
	ds_read_b64_tr_b16 v[76:77], v64 offset:0xc00
	ds_read_b64_tr_b16 v[78:79], v64 offset:0x600
	ds_read_b64_tr_b16 v[80:81], v64 offset:0xe00
	ds_read_b64_tr_b16 v[82:83], v64 offset:0x1000
	ds_read_b64_tr_b16 v[84:85], v64 offset:0x1800
	ds_read_b64_tr_b16 v[86:87], v64 offset:0x1200
	ds_read_b64_tr_b16 v[88:89], v64 offset:0x1a00
	s_waitcnt lgkmcnt(8)
	s_nop 0
	v_mfma_f32_32x32x16_bf16 v[48:63], v[156:159], v[66:69], v[48:63]
	ds_read_b64_tr_b16 v[66:67], v64 offset:0x1400
	ds_read_b64_tr_b16 v[68:69], v64 offset:0x1c00
	ds_read_b64_tr_b16 v[90:91], v64 offset:0x1600
	ds_read_b64_tr_b16 v[92:93], v64 offset:0x1e00
	s_waitcnt lgkmcnt(8)
	v_mfma_f32_32x32x16_bf16 v[32:47], v[156:159], v[70:73], v[32:47]
	v_mfma_f32_32x32x16_bf16 v[16:31], v[156:159], v[74:77], v[16:31]
	ds_read_b64_tr_b16 v[70:71], v64 offset:0x2000
	ds_read_b64_tr_b16 v[72:73], v64 offset:0x2800
	ds_read_b64_tr_b16 v[74:75], v64 offset:0x2200
	ds_read_b64_tr_b16 v[76:77], v64 offset:0x2a00
	s_waitcnt lgkmcnt(8)
	v_mfma_f32_32x32x16_bf16 v[0:15], v[156:159], v[78:81], v[0:15]
	v_mfma_f32_32x32x16_bf16 v[48:63], v[152:155], v[82:85], v[48:63]
	ds_read_b64_tr_b16 v[78:79], v64 offset:0x2400
	ds_read_b64_tr_b16 v[80:81], v64 offset:0x2c00
	ds_read_b64_tr_b16 v[82:83], v64 offset:0x2600
	ds_read_b64_tr_b16 v[84:85], v64 offset:0x2e00
	s_waitcnt lgkmcnt(8)
	v_mfma_f32_32x32x16_bf16 v[32:47], v[152:155], v[86:89], v[32:47]
	v_mfma_f32_32x32x16_bf16 v[16:31], v[152:155], v[66:69], v[16:31]
	ds_read_b64_tr_b16 v[66:67], v64 offset:0x3000
	ds_read_b64_tr_b16 v[68:69], v64 offset:0x3800
	ds_read_b64_tr_b16 v[86:87], v64 offset:0x3200
	ds_read_b64_tr_b16 v[88:89], v64 offset:0x3a00
	s_waitcnt lgkmcnt(8)
	v_mfma_f32_32x32x16_bf16 v[0:15], v[152:155], v[90:93], v[0:15]
	v_mfma_f32_32x32x16_bf16 v[48:63], v[148:151], v[70:73], v[48:63]
	ds_read_b64_tr_b16 v[70:71], v64 offset:0x3400
	ds_read_b64_tr_b16 v[72:73], v64 offset:0x3c00
	ds_read_b64_tr_b16 v[90:91], v64 offset:0x3600
	ds_read_b64_tr_b16 v[92:93], v64 offset:0x3e00
	s_waitcnt lgkmcnt(8)
	v_mfma_f32_32x32x16_bf16 v[32:47], v[148:151], v[74:77], v[32:47]
	v_mfma_f32_32x32x16_bf16 v[16:31], v[148:151], v[78:81], v[16:31]
	s_waitcnt lgkmcnt(4)
	v_mfma_f32_32x32x16_bf16 v[0:15], v[148:151], v[82:85], v[0:15]
	v_mfma_f32_32x32x16_bf16 v[48:63], v[144:147], v[66:69], v[48:63]
	s_waitcnt lgkmcnt(0)
	v_mfma_f32_32x32x16_bf16 v[32:47], v[144:147], v[86:89], v[32:47]
	v_mfma_f32_32x32x16_bf16 v[16:31], v[144:147], v[70:73], v[16:31]
	s_cmpk_lt_u32 s38, 0x100
	v_mfma_f32_32x32x16_bf16 v[0:15], v[144:147], v[90:93], v[0:15]
	s_cbranch_scc0 .LBB0_2091
	s_barrier
